# up-GEMM epilogue: 16-byte ACT stores (both column halves of a block stored together), masked edge weights formed on the fly
# speedup vs baseline: 1.0171x; 1.0005x over previous
.LBB0_186:
	v_readlane_b32 s76, v252, 59
	v_readlane_b32 s77, v252, 60
	v_cmp_eq_u32_e64 s[38:39], 0, v208
	v_cmp_eq_u32_e64 s[40:41], 15, v208
	v_readlane_b32 s4, v253, 18
	v_readlane_b32 s5, v253, 34
	v_readlane_b32 s8, v254, 59
	v_readlane_b32 s9, v254, 60
	v_readlane_b32 s14, v254, 55
	v_readlane_b32 s15, v254, 56
	v_readlane_b32 s42, v254, 61
	v_readlane_b32 s43, v254, 62
	v_readlane_b32 s94, v254, 57
	v_readlane_b32 s95, v254, 58
	s_lshl_b32 s6, s73, 9
	s_lshl_b32 s7, s4, 5
	s_add_i32 s7, s7, 0x20000
	v_lshl_add_u32 v144, v209, 3, s5
	v_mul_u32_u24_e32 v217, 0x2c00, v208
	v_lshl_add_u32 v196, v144, 2, s6
	v_lshl_add_u32 v197, v144, 2, s7
	v_lshl_add_u32 v217, v144, 1, v217
	s_add_u32 s26, s8, 0
	s_addc_u32 s27, s9, 0
	global_load_dwordx4 v[136:139], v196, s[26:27] offset:0
	s_add_u32 s26, s8, 22528
	s_addc_u32 s27, s9, 0
	global_load_dwordx4 v[140:143], v196, s[26:27] offset:0
	s_add_u32 s26, s14, 0
	s_addc_u32 s27, s15, 0
	global_load_dwordx4 v[150:153], v196, s[26:27] offset:0
	s_add_u32 s26, s14, 22528
	s_addc_u32 s27, s15, 0
	global_load_dwordx4 v[162:165], v196, s[26:27] offset:0
	s_add_u32 s26, s16, 0
	s_addc_u32 s27, s17, 0
	global_load_dwordx4 v[166:169], v196, s[26:27] offset:0
	s_add_u32 s26, s16, 22528
	s_addc_u32 s27, s17, 0
	global_load_dwordx4 v[170:173], v196, s[26:27] offset:0
	s_add_u32 s26, s42, 0
	s_addc_u32 s27, s43, 0
	global_load_dwordx4 v[174:177], v196, s[26:27] offset:0
	s_add_u32 s26, s42, 22528
	s_addc_u32 s27, s43, 0
	global_load_dwordx4 v[188:191], v196, s[26:27] offset:0
	s_lshl_b32 s6, s72, 8
	s_add_i32 s6, s6, s4
	s_mul_i32 s6, s6, 0x2c00
	s_add_u32 s94, s94, s6
	s_addc_u32 s95, s95, 0
	s_lshl_b32 s6, s73, 8
	s_add_u32 s94, s94, s6
	s_addc_u32 s95, s95, 0
	s_mov_b64 exec, s[38:39]
	ds_write_b128 v197, v[158:161] offset:0
	ds_write_b128 v197, v[62:65] offset:16
	ds_write_b128 v197, v[154:157] offset:512
	ds_write_b128 v197, v[58:61] offset:528
	ds_write_b128 v197, v[94:97] offset:4096
	ds_write_b128 v197, v[30:33] offset:4112
	ds_write_b128 v197, v[90:93] offset:4608
	ds_write_b128 v197, v[26:29] offset:4624
	s_mov_b64 exec, s[40:41]
	ds_write_b128 v197, v[102:105] offset:1024
	ds_write_b128 v197, v[38:41] offset:1040
	ds_write_b128 v197, v[98:101] offset:1536
	ds_write_b128 v197, v[34:37] offset:1552
	ds_write_b128 v197, v[66:69] offset:5120
	ds_write_b128 v197, v[2:5] offset:5136
	ds_write_b128 v197, v[70:73] offset:5632
	ds_write_b128 v197, v[6:9] offset:5648
	s_mov_b64 exec, -1
	v_add_u32_e32 v144, 0x800, v197
	v_add_u32_e32 v145, 0xfffffc00, v197
	v_cndmask_b32_e64 v246, v145, v144, s[40:41]
	s_cmp_eq_u32 s4, 0
	s_cselect_b64 vcc, -1, 0
	s_mov_b32 s6, 0xbfb8aa3b
	s_nop 0
	v_cndmask_b32_e32 v216, v246, v144, vcc
	s_cmp_eq_u32 s4, 64
	s_cselect_b64 vcc, -1, 0
	s_nop 1
	v_cndmask_b32_e32 v197, v246, v145, vcc
	s_waitcnt lgkmcnt(0)
	s_barrier
	ds_read_b128 v[192:195], v216 offset:0
	ds_read_b128 v[212:215], v216 offset:512
	s_waitcnt vmcnt(0)
	v_pk_fma_f32 v[238:239], v[150:151], v[158:159], v[174:175]
	v_pk_fma_f32 v[240:241], v[152:153], v[160:161], v[176:177]
	v_pk_fma_f32 v[242:243], v[162:163], v[154:155], v[188:189]
	v_pk_fma_f32 v[244:245], v[164:165], v[156:157], v[190:191]
	v_fmac_f32_dpp v238, v158, v136 row_shr:1 row_mask:0xf bank_mask:0xf
	v_fmac_f32_dpp v239, v159, v137 row_shr:1 row_mask:0xf bank_mask:0xf
	v_fmac_f32_dpp v240, v160, v138 row_shr:1 row_mask:0xf bank_mask:0xf
	v_fmac_f32_dpp v241, v161, v139 row_shr:1 row_mask:0xf bank_mask:0xf
	v_fmac_f32_dpp v242, v154, v140 row_shr:1 row_mask:0xf bank_mask:0xf
	v_fmac_f32_dpp v243, v155, v141 row_shr:1 row_mask:0xf bank_mask:0xf
	v_fmac_f32_dpp v244, v156, v142 row_shr:1 row_mask:0xf bank_mask:0xf
	v_fmac_f32_dpp v245, v157, v143 row_shr:1 row_mask:0xf bank_mask:0xf
	v_fmac_f32_dpp v238, v158, v166 row_shl:1 row_mask:0xf bank_mask:0xf
	v_fmac_f32_dpp v239, v159, v167 row_shl:1 row_mask:0xf bank_mask:0xf
	v_fmac_f32_dpp v240, v160, v168 row_shl:1 row_mask:0xf bank_mask:0xf
	v_fmac_f32_dpp v241, v161, v169 row_shl:1 row_mask:0xf bank_mask:0xf
	v_fmac_f32_dpp v242, v154, v170 row_shl:1 row_mask:0xf bank_mask:0xf
	v_fmac_f32_dpp v243, v155, v171 row_shl:1 row_mask:0xf bank_mask:0xf
	v_fmac_f32_dpp v244, v156, v172 row_shl:1 row_mask:0xf bank_mask:0xf
	v_fmac_f32_dpp v245, v157, v173 row_shl:1 row_mask:0xf bank_mask:0xf
	s_waitcnt lgkmcnt(0)
	s_cmp_eq_u32 s4, 0
	s_cbranch_scc1 .Lupc_1
	v_cndmask_b32_e64 v144, 0, v136, s[38:39]
	v_cndmask_b32_e64 v145, 0, v137, s[38:39]
	v_cndmask_b32_e64 v246, 0, v138, s[38:39]
	v_cndmask_b32_e64 v247, 0, v139, s[38:39]
	v_pk_fma_f32 v[238:239], v[192:193], v[144:145], v[238:239]
	v_pk_fma_f32 v[240:241], v[194:195], v[246:247], v[240:241]
	v_cndmask_b32_e64 v144, 0, v140, s[38:39]
	v_cndmask_b32_e64 v145, 0, v141, s[38:39]
	v_cndmask_b32_e64 v246, 0, v142, s[38:39]
	v_cndmask_b32_e64 v247, 0, v143, s[38:39]
	v_pk_fma_f32 v[242:243], v[212:213], v[144:145], v[242:243]
	v_pk_fma_f32 v[244:245], v[214:215], v[246:247], v[244:245]
.Lupc_1:
	v_cndmask_b32_e64 v144, 0, v166, s[40:41]
	v_cndmask_b32_e64 v145, 0, v167, s[40:41]
	v_cndmask_b32_e64 v246, 0, v168, s[40:41]
	v_cndmask_b32_e64 v247, 0, v169, s[40:41]
	v_fmac_f32_dpp v238, v146, v144 row_ror:15 row_mask:0xf bank_mask:0xf
	v_fmac_f32_dpp v239, v147, v145 row_ror:15 row_mask:0xf bank_mask:0xf
	v_fmac_f32_dpp v240, v148, v246 row_ror:15 row_mask:0xf bank_mask:0xf
	v_fmac_f32_dpp v241, v149, v247 row_ror:15 row_mask:0xf bank_mask:0xf
	v_cndmask_b32_e64 v144, 0, v170, s[40:41]
	v_cndmask_b32_e64 v145, 0, v171, s[40:41]
	v_cndmask_b32_e64 v246, 0, v172, s[40:41]
	v_cndmask_b32_e64 v247, 0, v173, s[40:41]
	v_fmac_f32_dpp v242, v114, v144 row_ror:15 row_mask:0xf bank_mask:0xf
	v_fmac_f32_dpp v243, v115, v145 row_ror:15 row_mask:0xf bank_mask:0xf
	v_fmac_f32_dpp v244, v116, v246 row_ror:15 row_mask:0xf bank_mask:0xf
	v_fmac_f32_dpp v245, v117, v247 row_ror:15 row_mask:0xf bank_mask:0xf
	s_cmp_lg_u32 s4, 0
	s_cbranch_scc1 .Lupc_2
	s_mov_b64 exec, s[38:39]
	s_lshl_b32 s7, s72, 1
	s_mul_i32 s7, s7, 0xb000
	v_readlane_b32 s26, v255, 0
	v_readlane_b32 s27, v255, 1
	s_add_u32 s26, s26, s7
	s_addc_u32 s27, s27, 0
	global_store_dwordx4 v196, v[158:161], s[26:27] offset:0
	s_add_u32 s26, s26, 22528
	s_addc_u32 s27, s27, 0
	global_store_dwordx4 v196, v[154:157], s[26:27] offset:0
	v_readlane_b32 s26, v255, 15
	v_readlane_b32 s27, v255, 16
	s_add_u32 s26, s26, s7
	s_addc_u32 s27, s27, 0
	global_store_dwordx4 v196, v[238:241], s[26:27] offset:0
	s_add_u32 s26, s26, 22528
	s_addc_u32 s27, s27, 0
	global_store_dwordx4 v196, v[242:245], s[26:27] offset:0
	s_mov_b64 exec, -1
.Lupc_2:
	v_pk_mul_f32 v[144:145], v[242:243], s[6:7] op_sel_hi:[1,0]
	v_pk_mul_f32 v[246:247], v[244:245], s[6:7] op_sel_hi:[1,0]
	v_exp_f32_e32 v144, v144
	v_exp_f32_e32 v145, v145
	v_exp_f32_e32 v246, v246
	v_exp_f32_e32 v247, v247
	v_add_f32_e32 v144, 1.0, v144
	v_add_f32_e32 v145, 1.0, v145
	v_add_f32_e32 v246, 1.0, v246
	v_add_f32_e32 v247, 1.0, v247
	v_rcp_f32_e32 v144, v144
	v_rcp_f32_e32 v145, v145
	v_rcp_f32_e32 v246, v246
	v_rcp_f32_e32 v247, v247
	s_nop 0
	v_pk_mul_f32 v[144:145], v[242:243], v[144:145]
	v_pk_mul_f32 v[246:247], v[244:245], v[246:247]
	v_pk_mul_f32 v[144:145], v[238:239], v[144:145]
	v_pk_mul_f32 v[246:247], v[240:241], v[246:247]
	v_cvt_pk_bf16_f32 v118, v144, v145
	v_cvt_pk_bf16_f32 v119, v246, v247
	v_pk_fma_f32 v[238:239], v[150:151], v[146:147], v[174:175]
	v_pk_fma_f32 v[240:241], v[152:153], v[148:149], v[176:177]
	v_pk_fma_f32 v[242:243], v[162:163], v[114:115], v[188:189]
	v_pk_fma_f32 v[244:245], v[164:165], v[116:117], v[190:191]
	v_fmac_f32_dpp v238, v146, v136 row_shr:1 row_mask:0xf bank_mask:0xf
	v_fmac_f32_dpp v239, v147, v137 row_shr:1 row_mask:0xf bank_mask:0xf
	v_fmac_f32_dpp v240, v148, v138 row_shr:1 row_mask:0xf bank_mask:0xf
	v_fmac_f32_dpp v241, v149, v139 row_shr:1 row_mask:0xf bank_mask:0xf
	v_fmac_f32_dpp v242, v114, v140 row_shr:1 row_mask:0xf bank_mask:0xf
	v_fmac_f32_dpp v243, v115, v141 row_shr:1 row_mask:0xf bank_mask:0xf
	v_fmac_f32_dpp v244, v116, v142 row_shr:1 row_mask:0xf bank_mask:0xf
	v_fmac_f32_dpp v245, v117, v143 row_shr:1 row_mask:0xf bank_mask:0xf
	v_fmac_f32_dpp v238, v146, v166 row_shl:1 row_mask:0xf bank_mask:0xf
	v_fmac_f32_dpp v239, v147, v167 row_shl:1 row_mask:0xf bank_mask:0xf
	v_fmac_f32_dpp v240, v148, v168 row_shl:1 row_mask:0xf bank_mask:0xf
	v_fmac_f32_dpp v241, v149, v169 row_shl:1 row_mask:0xf bank_mask:0xf
	v_fmac_f32_dpp v242, v114, v170 row_shl:1 row_mask:0xf bank_mask:0xf
	v_fmac_f32_dpp v243, v115, v171 row_shl:1 row_mask:0xf bank_mask:0xf
	v_fmac_f32_dpp v244, v116, v172 row_shl:1 row_mask:0xf bank_mask:0xf
	v_fmac_f32_dpp v245, v117, v173 row_shl:1 row_mask:0xf bank_mask:0xf
	v_cndmask_b32_e64 v144, 0, v136, s[38:39]
	v_cndmask_b32_e64 v145, 0, v137, s[38:39]
	v_cndmask_b32_e64 v246, 0, v138, s[38:39]
	v_cndmask_b32_e64 v247, 0, v139, s[38:39]
	v_fmac_f32_dpp v238, v158, v144 row_ror:1 row_mask:0xf bank_mask:0xf
	v_fmac_f32_dpp v239, v159, v145 row_ror:1 row_mask:0xf bank_mask:0xf
	v_fmac_f32_dpp v240, v160, v246 row_ror:1 row_mask:0xf bank_mask:0xf
	v_fmac_f32_dpp v241, v161, v247 row_ror:1 row_mask:0xf bank_mask:0xf
	v_cndmask_b32_e64 v144, 0, v140, s[38:39]
	v_cndmask_b32_e64 v145, 0, v141, s[38:39]
	v_cndmask_b32_e64 v246, 0, v142, s[38:39]
	v_cndmask_b32_e64 v247, 0, v143, s[38:39]
	v_fmac_f32_dpp v242, v154, v144 row_ror:1 row_mask:0xf bank_mask:0xf
	v_fmac_f32_dpp v243, v155, v145 row_ror:1 row_mask:0xf bank_mask:0xf
	v_fmac_f32_dpp v244, v156, v246 row_ror:1 row_mask:0xf bank_mask:0xf
	v_fmac_f32_dpp v245, v157, v247 row_ror:1 row_mask:0xf bank_mask:0xf
	v_cndmask_b32_e64 v144, 0, v166, s[40:41]
	v_cndmask_b32_e64 v145, 0, v167, s[40:41]
	v_cndmask_b32_e64 v246, 0, v168, s[40:41]
	v_cndmask_b32_e64 v247, 0, v169, s[40:41]
	v_fmac_f32_dpp v238, v110, v144 row_ror:15 row_mask:0xf bank_mask:0xf
	v_fmac_f32_dpp v239, v111, v145 row_ror:15 row_mask:0xf bank_mask:0xf
	v_fmac_f32_dpp v240, v112, v246 row_ror:15 row_mask:0xf bank_mask:0xf
	v_fmac_f32_dpp v241, v113, v247 row_ror:15 row_mask:0xf bank_mask:0xf
	v_cndmask_b32_e64 v144, 0, v170, s[40:41]
	v_cndmask_b32_e64 v145, 0, v171, s[40:41]
	v_cndmask_b32_e64 v246, 0, v172, s[40:41]
	v_cndmask_b32_e64 v247, 0, v173, s[40:41]
	v_fmac_f32_dpp v242, v106, v144 row_ror:15 row_mask:0xf bank_mask:0xf
	v_fmac_f32_dpp v243, v107, v145 row_ror:15 row_mask:0xf bank_mask:0xf
	v_fmac_f32_dpp v244, v108, v246 row_ror:15 row_mask:0xf bank_mask:0xf
	v_fmac_f32_dpp v245, v109, v247 row_ror:15 row_mask:0xf bank_mask:0xf
	v_pk_mul_f32 v[144:145], v[242:243], s[6:7] op_sel_hi:[1,0]
	v_pk_mul_f32 v[246:247], v[244:245], s[6:7] op_sel_hi:[1,0]
	v_exp_f32_e32 v144, v144
	v_exp_f32_e32 v145, v145
	v_exp_f32_e32 v246, v246
	v_exp_f32_e32 v247, v247
	v_add_f32_e32 v144, 1.0, v144
	v_add_f32_e32 v145, 1.0, v145
	v_add_f32_e32 v246, 1.0, v246
	v_add_f32_e32 v247, 1.0, v247
	v_rcp_f32_e32 v144, v144
	v_rcp_f32_e32 v145, v145
	v_rcp_f32_e32 v246, v246
	v_rcp_f32_e32 v247, v247
	s_nop 0
	v_pk_mul_f32 v[144:145], v[242:243], v[144:145]
	v_pk_mul_f32 v[246:247], v[244:245], v[246:247]
	v_pk_mul_f32 v[144:145], v[238:239], v[144:145]
	v_pk_mul_f32 v[246:247], v[240:241], v[246:247]
	v_cvt_pk_bf16_f32 v120, v144, v145
	v_cvt_pk_bf16_f32 v121, v246, v247
	v_pk_fma_f32 v[238:239], v[150:151], v[110:111], v[174:175]
	v_pk_fma_f32 v[240:241], v[152:153], v[112:113], v[176:177]
	v_pk_fma_f32 v[242:243], v[162:163], v[106:107], v[188:189]
	v_pk_fma_f32 v[244:245], v[164:165], v[108:109], v[190:191]
	v_fmac_f32_dpp v238, v110, v136 row_shr:1 row_mask:0xf bank_mask:0xf
	v_fmac_f32_dpp v239, v111, v137 row_shr:1 row_mask:0xf bank_mask:0xf
	v_fmac_f32_dpp v240, v112, v138 row_shr:1 row_mask:0xf bank_mask:0xf
	v_fmac_f32_dpp v241, v113, v139 row_shr:1 row_mask:0xf bank_mask:0xf
	v_fmac_f32_dpp v242, v106, v140 row_shr:1 row_mask:0xf bank_mask:0xf
	v_fmac_f32_dpp v243, v107, v141 row_shr:1 row_mask:0xf bank_mask:0xf
	v_fmac_f32_dpp v244, v108, v142 row_shr:1 row_mask:0xf bank_mask:0xf
	v_fmac_f32_dpp v245, v109, v143 row_shr:1 row_mask:0xf bank_mask:0xf
	v_fmac_f32_dpp v238, v110, v166 row_shl:1 row_mask:0xf bank_mask:0xf
	v_fmac_f32_dpp v239, v111, v167 row_shl:1 row_mask:0xf bank_mask:0xf
	v_fmac_f32_dpp v240, v112, v168 row_shl:1 row_mask:0xf bank_mask:0xf
	v_fmac_f32_dpp v241, v113, v169 row_shl:1 row_mask:0xf bank_mask:0xf
	v_fmac_f32_dpp v242, v106, v170 row_shl:1 row_mask:0xf bank_mask:0xf
	v_fmac_f32_dpp v243, v107, v171 row_shl:1 row_mask:0xf bank_mask:0xf
	v_fmac_f32_dpp v244, v108, v172 row_shl:1 row_mask:0xf bank_mask:0xf
	v_fmac_f32_dpp v245, v109, v173 row_shl:1 row_mask:0xf bank_mask:0xf
	v_cndmask_b32_e64 v144, 0, v136, s[38:39]
	v_cndmask_b32_e64 v145, 0, v137, s[38:39]
	v_cndmask_b32_e64 v246, 0, v138, s[38:39]
	v_cndmask_b32_e64 v247, 0, v139, s[38:39]
	v_fmac_f32_dpp v238, v146, v144 row_ror:1 row_mask:0xf bank_mask:0xf
	v_fmac_f32_dpp v239, v147, v145 row_ror:1 row_mask:0xf bank_mask:0xf
	v_fmac_f32_dpp v240, v148, v246 row_ror:1 row_mask:0xf bank_mask:0xf
	v_fmac_f32_dpp v241, v149, v247 row_ror:1 row_mask:0xf bank_mask:0xf
	v_cndmask_b32_e64 v144, 0, v140, s[38:39]
	v_cndmask_b32_e64 v145, 0, v141, s[38:39]
	v_cndmask_b32_e64 v246, 0, v142, s[38:39]
	v_cndmask_b32_e64 v247, 0, v143, s[38:39]
	v_fmac_f32_dpp v242, v114, v144 row_ror:1 row_mask:0xf bank_mask:0xf
	v_fmac_f32_dpp v243, v115, v145 row_ror:1 row_mask:0xf bank_mask:0xf
	v_fmac_f32_dpp v244, v116, v246 row_ror:1 row_mask:0xf bank_mask:0xf
	v_fmac_f32_dpp v245, v117, v247 row_ror:1 row_mask:0xf bank_mask:0xf
	v_cndmask_b32_e64 v144, 0, v166, s[40:41]
	v_cndmask_b32_e64 v145, 0, v167, s[40:41]
	v_cndmask_b32_e64 v246, 0, v168, s[40:41]
	v_cndmask_b32_e64 v247, 0, v169, s[40:41]
	v_fmac_f32_dpp v238, v102, v144 row_ror:15 row_mask:0xf bank_mask:0xf
	v_fmac_f32_dpp v239, v103, v145 row_ror:15 row_mask:0xf bank_mask:0xf
	v_fmac_f32_dpp v240, v104, v246 row_ror:15 row_mask:0xf bank_mask:0xf
	v_fmac_f32_dpp v241, v105, v247 row_ror:15 row_mask:0xf bank_mask:0xf
	v_cndmask_b32_e64 v144, 0, v170, s[40:41]
	v_cndmask_b32_e64 v145, 0, v171, s[40:41]
	v_cndmask_b32_e64 v246, 0, v172, s[40:41]
	v_cndmask_b32_e64 v247, 0, v173, s[40:41]
	v_fmac_f32_dpp v242, v98, v144 row_ror:15 row_mask:0xf bank_mask:0xf
	v_fmac_f32_dpp v243, v99, v145 row_ror:15 row_mask:0xf bank_mask:0xf
	v_fmac_f32_dpp v244, v100, v246 row_ror:15 row_mask:0xf bank_mask:0xf
	v_fmac_f32_dpp v245, v101, v247 row_ror:15 row_mask:0xf bank_mask:0xf
	v_pk_mul_f32 v[144:145], v[242:243], s[6:7] op_sel_hi:[1,0]
	v_pk_mul_f32 v[246:247], v[244:245], s[6:7] op_sel_hi:[1,0]
	v_exp_f32_e32 v144, v144
	v_exp_f32_e32 v145, v145
	v_exp_f32_e32 v246, v246
	v_exp_f32_e32 v247, v247
	v_add_f32_e32 v144, 1.0, v144
	v_add_f32_e32 v145, 1.0, v145
	v_add_f32_e32 v246, 1.0, v246
	v_add_f32_e32 v247, 1.0, v247
	v_rcp_f32_e32 v144, v144
	v_rcp_f32_e32 v145, v145
	v_rcp_f32_e32 v246, v246
	v_rcp_f32_e32 v247, v247
	s_nop 0
	v_pk_mul_f32 v[144:145], v[242:243], v[144:145]
	v_pk_mul_f32 v[246:247], v[244:245], v[246:247]
	v_pk_mul_f32 v[144:145], v[238:239], v[144:145]
	v_pk_mul_f32 v[246:247], v[240:241], v[246:247]
	v_cvt_pk_bf16_f32 v122, v144, v145
	v_cvt_pk_bf16_f32 v123, v246, v247
	v_pk_fma_f32 v[238:239], v[150:151], v[102:103], v[174:175]
	v_pk_fma_f32 v[240:241], v[152:153], v[104:105], v[176:177]
	v_pk_fma_f32 v[242:243], v[162:163], v[98:99], v[188:189]
	v_pk_fma_f32 v[244:245], v[164:165], v[100:101], v[190:191]
	v_fmac_f32_dpp v238, v102, v136 row_shr:1 row_mask:0xf bank_mask:0xf
	v_fmac_f32_dpp v239, v103, v137 row_shr:1 row_mask:0xf bank_mask:0xf
	v_fmac_f32_dpp v240, v104, v138 row_shr:1 row_mask:0xf bank_mask:0xf
	v_fmac_f32_dpp v241, v105, v139 row_shr:1 row_mask:0xf bank_mask:0xf
	v_fmac_f32_dpp v242, v98, v140 row_shr:1 row_mask:0xf bank_mask:0xf
	v_fmac_f32_dpp v243, v99, v141 row_shr:1 row_mask:0xf bank_mask:0xf
	v_fmac_f32_dpp v244, v100, v142 row_shr:1 row_mask:0xf bank_mask:0xf
	v_fmac_f32_dpp v245, v101, v143 row_shr:1 row_mask:0xf bank_mask:0xf
	v_fmac_f32_dpp v238, v102, v166 row_shl:1 row_mask:0xf bank_mask:0xf
	v_fmac_f32_dpp v239, v103, v167 row_shl:1 row_mask:0xf bank_mask:0xf
	v_fmac_f32_dpp v240, v104, v168 row_shl:1 row_mask:0xf bank_mask:0xf
	v_fmac_f32_dpp v241, v105, v169 row_shl:1 row_mask:0xf bank_mask:0xf
	v_fmac_f32_dpp v242, v98, v170 row_shl:1 row_mask:0xf bank_mask:0xf
	v_fmac_f32_dpp v243, v99, v171 row_shl:1 row_mask:0xf bank_mask:0xf
	v_fmac_f32_dpp v244, v100, v172 row_shl:1 row_mask:0xf bank_mask:0xf
	v_fmac_f32_dpp v245, v101, v173 row_shl:1 row_mask:0xf bank_mask:0xf
	v_cndmask_b32_e64 v144, 0, v136, s[38:39]
	v_cndmask_b32_e64 v145, 0, v137, s[38:39]
	v_cndmask_b32_e64 v246, 0, v138, s[38:39]
	v_cndmask_b32_e64 v247, 0, v139, s[38:39]
	v_fmac_f32_dpp v238, v110, v144 row_ror:1 row_mask:0xf bank_mask:0xf
	v_fmac_f32_dpp v239, v111, v145 row_ror:1 row_mask:0xf bank_mask:0xf
	v_fmac_f32_dpp v240, v112, v246 row_ror:1 row_mask:0xf bank_mask:0xf
	v_fmac_f32_dpp v241, v113, v247 row_ror:1 row_mask:0xf bank_mask:0xf
	v_cndmask_b32_e64 v144, 0, v140, s[38:39]
	v_cndmask_b32_e64 v145, 0, v141, s[38:39]
	v_cndmask_b32_e64 v246, 0, v142, s[38:39]
	v_cndmask_b32_e64 v247, 0, v143, s[38:39]
	v_fmac_f32_dpp v242, v106, v144 row_ror:1 row_mask:0xf bank_mask:0xf
	v_fmac_f32_dpp v243, v107, v145 row_ror:1 row_mask:0xf bank_mask:0xf
	v_fmac_f32_dpp v244, v108, v246 row_ror:1 row_mask:0xf bank_mask:0xf
	v_fmac_f32_dpp v245, v109, v247 row_ror:1 row_mask:0xf bank_mask:0xf
	s_waitcnt lgkmcnt(0)
	v_cndmask_b32_e64 v144, 0, v166, s[40:41]
	v_cndmask_b32_e64 v145, 0, v167, s[40:41]
	v_cndmask_b32_e64 v246, 0, v168, s[40:41]
	v_cndmask_b32_e64 v247, 0, v169, s[40:41]
	v_pk_fma_f32 v[238:239], v[192:193], v[144:145], v[238:239]
	v_pk_fma_f32 v[240:241], v[194:195], v[246:247], v[240:241]
	v_cndmask_b32_e64 v144, 0, v170, s[40:41]
	v_cndmask_b32_e64 v145, 0, v171, s[40:41]
	v_cndmask_b32_e64 v246, 0, v172, s[40:41]
	v_cndmask_b32_e64 v247, 0, v173, s[40:41]
	v_pk_fma_f32 v[242:243], v[212:213], v[144:145], v[242:243]
	v_pk_fma_f32 v[244:245], v[214:215], v[246:247], v[244:245]
	v_pk_mul_f32 v[144:145], v[242:243], s[6:7] op_sel_hi:[1,0]
	v_pk_mul_f32 v[246:247], v[244:245], s[6:7] op_sel_hi:[1,0]
	v_exp_f32_e32 v144, v144
	v_exp_f32_e32 v145, v145
	v_exp_f32_e32 v246, v246
	v_exp_f32_e32 v247, v247
	v_add_f32_e32 v144, 1.0, v144
	v_add_f32_e32 v145, 1.0, v145
	v_add_f32_e32 v246, 1.0, v246
	v_add_f32_e32 v247, 1.0, v247
	v_rcp_f32_e32 v144, v144
	v_rcp_f32_e32 v145, v145
	v_rcp_f32_e32 v246, v246
	v_rcp_f32_e32 v247, v247
	s_nop 0
	v_pk_mul_f32 v[144:145], v[242:243], v[144:145]
	v_pk_mul_f32 v[246:247], v[244:245], v[246:247]
	v_pk_mul_f32 v[144:145], v[238:239], v[144:145]
	v_pk_mul_f32 v[246:247], v[240:241], v[246:247]
	v_cvt_pk_bf16_f32 v124, v144, v145
	v_cvt_pk_bf16_f32 v125, v246, v247
	s_add_u32 s26, s8, 0
	s_addc_u32 s27, s9, 0
	global_load_dwordx4 v[158:161], v196, s[26:27] offset:16
	s_add_u32 s26, s8, 22528
	s_addc_u32 s27, s9, 0
	global_load_dwordx4 v[154:157], v196, s[26:27] offset:16
	s_add_u32 s26, s14, 0
	s_addc_u32 s27, s15, 0
	global_load_dwordx4 v[146:149], v196, s[26:27] offset:16
	s_add_u32 s26, s14, 22528
	s_addc_u32 s27, s15, 0
	global_load_dwordx4 v[114:117], v196, s[26:27] offset:16
	s_add_u32 s26, s16, 0
	s_addc_u32 s27, s17, 0
	global_load_dwordx4 v[110:113], v196, s[26:27] offset:16
	s_add_u32 s26, s16, 22528
	s_addc_u32 s27, s17, 0
	global_load_dwordx4 v[106:109], v196, s[26:27] offset:16
	s_add_u32 s26, s42, 0
	s_addc_u32 s27, s43, 0
	global_load_dwordx4 v[102:105], v196, s[26:27] offset:16
	s_add_u32 s26, s42, 22528
	s_addc_u32 s27, s43, 0
	global_load_dwordx4 v[98:101], v196, s[26:27] offset:16
	ds_read_b128 v[192:195], v197 offset:4096
	ds_read_b128 v[212:215], v197 offset:4608
	v_pk_fma_f32 v[238:239], v[150:151], v[94:95], v[174:175]
	v_pk_fma_f32 v[240:241], v[152:153], v[96:97], v[176:177]
	v_pk_fma_f32 v[242:243], v[162:163], v[90:91], v[188:189]
	v_pk_fma_f32 v[244:245], v[164:165], v[92:93], v[190:191]
	v_fmac_f32_dpp v238, v94, v136 row_shr:1 row_mask:0xf bank_mask:0xf
	v_fmac_f32_dpp v239, v95, v137 row_shr:1 row_mask:0xf bank_mask:0xf
	v_fmac_f32_dpp v240, v96, v138 row_shr:1 row_mask:0xf bank_mask:0xf
	v_fmac_f32_dpp v241, v97, v139 row_shr:1 row_mask:0xf bank_mask:0xf
	v_fmac_f32_dpp v242, v90, v140 row_shr:1 row_mask:0xf bank_mask:0xf
	v_fmac_f32_dpp v243, v91, v141 row_shr:1 row_mask:0xf bank_mask:0xf
	v_fmac_f32_dpp v244, v92, v142 row_shr:1 row_mask:0xf bank_mask:0xf
	v_fmac_f32_dpp v245, v93, v143 row_shr:1 row_mask:0xf bank_mask:0xf
	v_fmac_f32_dpp v238, v94, v166 row_shl:1 row_mask:0xf bank_mask:0xf
	v_fmac_f32_dpp v239, v95, v167 row_shl:1 row_mask:0xf bank_mask:0xf
	v_fmac_f32_dpp v240, v96, v168 row_shl:1 row_mask:0xf bank_mask:0xf
	v_fmac_f32_dpp v241, v97, v169 row_shl:1 row_mask:0xf bank_mask:0xf
	v_fmac_f32_dpp v242, v90, v170 row_shl:1 row_mask:0xf bank_mask:0xf
	v_fmac_f32_dpp v243, v91, v171 row_shl:1 row_mask:0xf bank_mask:0xf
	v_fmac_f32_dpp v244, v92, v172 row_shl:1 row_mask:0xf bank_mask:0xf
	v_fmac_f32_dpp v245, v93, v173 row_shl:1 row_mask:0xf bank_mask:0xf
	s_waitcnt lgkmcnt(0)
	v_cndmask_b32_e64 v144, 0, v136, s[38:39]
	v_cndmask_b32_e64 v145, 0, v137, s[38:39]
	v_cndmask_b32_e64 v246, 0, v138, s[38:39]
	v_cndmask_b32_e64 v247, 0, v139, s[38:39]
	v_pk_fma_f32 v[238:239], v[192:193], v[144:145], v[238:239]
	v_pk_fma_f32 v[240:241], v[194:195], v[246:247], v[240:241]
	v_cndmask_b32_e64 v144, 0, v140, s[38:39]
	v_cndmask_b32_e64 v145, 0, v141, s[38:39]
	v_cndmask_b32_e64 v246, 0, v142, s[38:39]
	v_cndmask_b32_e64 v247, 0, v143, s[38:39]
	v_pk_fma_f32 v[242:243], v[212:213], v[144:145], v[242:243]
	v_pk_fma_f32 v[244:245], v[214:215], v[246:247], v[244:245]
	v_cndmask_b32_e64 v144, 0, v166, s[40:41]
	v_cndmask_b32_e64 v145, 0, v167, s[40:41]
	v_cndmask_b32_e64 v246, 0, v168, s[40:41]
	v_cndmask_b32_e64 v247, 0, v169, s[40:41]
	v_fmac_f32_dpp v238, v86, v144 row_ror:15 row_mask:0xf bank_mask:0xf
	v_fmac_f32_dpp v239, v87, v145 row_ror:15 row_mask:0xf bank_mask:0xf
	v_fmac_f32_dpp v240, v88, v246 row_ror:15 row_mask:0xf bank_mask:0xf
	v_fmac_f32_dpp v241, v89, v247 row_ror:15 row_mask:0xf bank_mask:0xf
	v_cndmask_b32_e64 v144, 0, v170, s[40:41]
	v_cndmask_b32_e64 v145, 0, v171, s[40:41]
	v_cndmask_b32_e64 v246, 0, v172, s[40:41]
	v_cndmask_b32_e64 v247, 0, v173, s[40:41]
	v_fmac_f32_dpp v242, v82, v144 row_ror:15 row_mask:0xf bank_mask:0xf
	v_fmac_f32_dpp v243, v83, v145 row_ror:15 row_mask:0xf bank_mask:0xf
	v_fmac_f32_dpp v244, v84, v246 row_ror:15 row_mask:0xf bank_mask:0xf
	v_fmac_f32_dpp v245, v85, v247 row_ror:15 row_mask:0xf bank_mask:0xf
	v_pk_mul_f32 v[144:145], v[242:243], s[6:7] op_sel_hi:[1,0]
	v_pk_mul_f32 v[246:247], v[244:245], s[6:7] op_sel_hi:[1,0]
	v_exp_f32_e32 v144, v144
	v_exp_f32_e32 v145, v145
	v_exp_f32_e32 v246, v246
	v_exp_f32_e32 v247, v247
	v_add_f32_e32 v144, 1.0, v144
	v_add_f32_e32 v145, 1.0, v145
	v_add_f32_e32 v246, 1.0, v246
	v_add_f32_e32 v247, 1.0, v247
	v_rcp_f32_e32 v144, v144
	v_rcp_f32_e32 v145, v145
	v_rcp_f32_e32 v246, v246
	v_rcp_f32_e32 v247, v247
	s_nop 0
	v_pk_mul_f32 v[144:145], v[242:243], v[144:145]
	v_pk_mul_f32 v[246:247], v[244:245], v[246:247]
	v_pk_mul_f32 v[144:145], v[238:239], v[144:145]
	v_pk_mul_f32 v[246:247], v[240:241], v[246:247]
	v_cvt_pk_bf16_f32 v126, v144, v145
	v_cvt_pk_bf16_f32 v127, v246, v247
	v_pk_fma_f32 v[238:239], v[150:151], v[86:87], v[174:175]
	v_pk_fma_f32 v[240:241], v[152:153], v[88:89], v[176:177]
	v_pk_fma_f32 v[242:243], v[162:163], v[82:83], v[188:189]
	v_pk_fma_f32 v[244:245], v[164:165], v[84:85], v[190:191]
	v_fmac_f32_dpp v238, v86, v136 row_shr:1 row_mask:0xf bank_mask:0xf
	v_fmac_f32_dpp v239, v87, v137 row_shr:1 row_mask:0xf bank_mask:0xf
	v_fmac_f32_dpp v240, v88, v138 row_shr:1 row_mask:0xf bank_mask:0xf
	v_fmac_f32_dpp v241, v89, v139 row_shr:1 row_mask:0xf bank_mask:0xf
	v_fmac_f32_dpp v242, v82, v140 row_shr:1 row_mask:0xf bank_mask:0xf
	v_fmac_f32_dpp v243, v83, v141 row_shr:1 row_mask:0xf bank_mask:0xf
	v_fmac_f32_dpp v244, v84, v142 row_shr:1 row_mask:0xf bank_mask:0xf
	v_fmac_f32_dpp v245, v85, v143 row_shr:1 row_mask:0xf bank_mask:0xf
	v_fmac_f32_dpp v238, v86, v166 row_shl:1 row_mask:0xf bank_mask:0xf
	v_fmac_f32_dpp v239, v87, v167 row_shl:1 row_mask:0xf bank_mask:0xf
	v_fmac_f32_dpp v240, v88, v168 row_shl:1 row_mask:0xf bank_mask:0xf
	v_fmac_f32_dpp v241, v89, v169 row_shl:1 row_mask:0xf bank_mask:0xf
	v_fmac_f32_dpp v242, v82, v170 row_shl:1 row_mask:0xf bank_mask:0xf
	v_fmac_f32_dpp v243, v83, v171 row_shl:1 row_mask:0xf bank_mask:0xf
	v_fmac_f32_dpp v244, v84, v172 row_shl:1 row_mask:0xf bank_mask:0xf
	v_fmac_f32_dpp v245, v85, v173 row_shl:1 row_mask:0xf bank_mask:0xf
	v_cndmask_b32_e64 v144, 0, v136, s[38:39]
	v_cndmask_b32_e64 v145, 0, v137, s[38:39]
	v_cndmask_b32_e64 v246, 0, v138, s[38:39]
	v_cndmask_b32_e64 v247, 0, v139, s[38:39]
	v_fmac_f32_dpp v238, v94, v144 row_ror:1 row_mask:0xf bank_mask:0xf
	v_fmac_f32_dpp v239, v95, v145 row_ror:1 row_mask:0xf bank_mask:0xf
	v_fmac_f32_dpp v240, v96, v246 row_ror:1 row_mask:0xf bank_mask:0xf
	v_fmac_f32_dpp v241, v97, v247 row_ror:1 row_mask:0xf bank_mask:0xf
	v_cndmask_b32_e64 v144, 0, v140, s[38:39]
	v_cndmask_b32_e64 v145, 0, v141, s[38:39]
	v_cndmask_b32_e64 v246, 0, v142, s[38:39]
	v_cndmask_b32_e64 v247, 0, v143, s[38:39]
	v_fmac_f32_dpp v242, v90, v144 row_ror:1 row_mask:0xf bank_mask:0xf
	v_fmac_f32_dpp v243, v91, v145 row_ror:1 row_mask:0xf bank_mask:0xf
	v_fmac_f32_dpp v244, v92, v246 row_ror:1 row_mask:0xf bank_mask:0xf
	v_fmac_f32_dpp v245, v93, v247 row_ror:1 row_mask:0xf bank_mask:0xf
	v_cndmask_b32_e64 v144, 0, v166, s[40:41]
	v_cndmask_b32_e64 v145, 0, v167, s[40:41]
	v_cndmask_b32_e64 v246, 0, v168, s[40:41]
	v_cndmask_b32_e64 v247, 0, v169, s[40:41]
	v_fmac_f32_dpp v238, v78, v144 row_ror:15 row_mask:0xf bank_mask:0xf
	v_fmac_f32_dpp v239, v79, v145 row_ror:15 row_mask:0xf bank_mask:0xf
	v_fmac_f32_dpp v240, v80, v246 row_ror:15 row_mask:0xf bank_mask:0xf
	v_fmac_f32_dpp v241, v81, v247 row_ror:15 row_mask:0xf bank_mask:0xf
	v_cndmask_b32_e64 v144, 0, v170, s[40:41]
	v_cndmask_b32_e64 v145, 0, v171, s[40:41]
	v_cndmask_b32_e64 v246, 0, v172, s[40:41]
	v_cndmask_b32_e64 v247, 0, v173, s[40:41]
	v_fmac_f32_dpp v242, v74, v144 row_ror:15 row_mask:0xf bank_mask:0xf
	v_fmac_f32_dpp v243, v75, v145 row_ror:15 row_mask:0xf bank_mask:0xf
	v_fmac_f32_dpp v244, v76, v246 row_ror:15 row_mask:0xf bank_mask:0xf
	v_fmac_f32_dpp v245, v77, v247 row_ror:15 row_mask:0xf bank_mask:0xf
	v_pk_mul_f32 v[144:145], v[242:243], s[6:7] op_sel_hi:[1,0]
	v_pk_mul_f32 v[246:247], v[244:245], s[6:7] op_sel_hi:[1,0]
	v_exp_f32_e32 v144, v144
	v_exp_f32_e32 v145, v145
	v_exp_f32_e32 v246, v246
	v_exp_f32_e32 v247, v247
	v_add_f32_e32 v144, 1.0, v144
	v_add_f32_e32 v145, 1.0, v145
	v_add_f32_e32 v246, 1.0, v246
	v_add_f32_e32 v247, 1.0, v247
	v_rcp_f32_e32 v144, v144
	v_rcp_f32_e32 v145, v145
	v_rcp_f32_e32 v246, v246
	v_rcp_f32_e32 v247, v247
	s_nop 0
	v_pk_mul_f32 v[144:145], v[242:243], v[144:145]
	v_pk_mul_f32 v[246:247], v[244:245], v[246:247]
	v_pk_mul_f32 v[144:145], v[238:239], v[144:145]
	v_pk_mul_f32 v[246:247], v[240:241], v[246:247]
	v_cvt_pk_bf16_f32 v128, v144, v145
	v_cvt_pk_bf16_f32 v129, v246, v247
	v_pk_fma_f32 v[238:239], v[150:151], v[78:79], v[174:175]
	v_pk_fma_f32 v[240:241], v[152:153], v[80:81], v[176:177]
	v_pk_fma_f32 v[242:243], v[162:163], v[74:75], v[188:189]
	v_pk_fma_f32 v[244:245], v[164:165], v[76:77], v[190:191]
	v_fmac_f32_dpp v238, v78, v136 row_shr:1 row_mask:0xf bank_mask:0xf
	v_fmac_f32_dpp v239, v79, v137 row_shr:1 row_mask:0xf bank_mask:0xf
	v_fmac_f32_dpp v240, v80, v138 row_shr:1 row_mask:0xf bank_mask:0xf
	v_fmac_f32_dpp v241, v81, v139 row_shr:1 row_mask:0xf bank_mask:0xf
	v_fmac_f32_dpp v242, v74, v140 row_shr:1 row_mask:0xf bank_mask:0xf
	v_fmac_f32_dpp v243, v75, v141 row_shr:1 row_mask:0xf bank_mask:0xf
	v_fmac_f32_dpp v244, v76, v142 row_shr:1 row_mask:0xf bank_mask:0xf
	v_fmac_f32_dpp v245, v77, v143 row_shr:1 row_mask:0xf bank_mask:0xf
	v_fmac_f32_dpp v238, v78, v166 row_shl:1 row_mask:0xf bank_mask:0xf
	v_fmac_f32_dpp v239, v79, v167 row_shl:1 row_mask:0xf bank_mask:0xf
	v_fmac_f32_dpp v240, v80, v168 row_shl:1 row_mask:0xf bank_mask:0xf
	v_fmac_f32_dpp v241, v81, v169 row_shl:1 row_mask:0xf bank_mask:0xf
	v_fmac_f32_dpp v242, v74, v170 row_shl:1 row_mask:0xf bank_mask:0xf
	v_fmac_f32_dpp v243, v75, v171 row_shl:1 row_mask:0xf bank_mask:0xf
	v_fmac_f32_dpp v244, v76, v172 row_shl:1 row_mask:0xf bank_mask:0xf
	v_fmac_f32_dpp v245, v77, v173 row_shl:1 row_mask:0xf bank_mask:0xf
	v_cndmask_b32_e64 v144, 0, v136, s[38:39]
	v_cndmask_b32_e64 v145, 0, v137, s[38:39]
	v_cndmask_b32_e64 v246, 0, v138, s[38:39]
	v_cndmask_b32_e64 v247, 0, v139, s[38:39]
	v_fmac_f32_dpp v238, v86, v144 row_ror:1 row_mask:0xf bank_mask:0xf
	v_fmac_f32_dpp v239, v87, v145 row_ror:1 row_mask:0xf bank_mask:0xf
	v_fmac_f32_dpp v240, v88, v246 row_ror:1 row_mask:0xf bank_mask:0xf
	v_fmac_f32_dpp v241, v89, v247 row_ror:1 row_mask:0xf bank_mask:0xf
	v_cndmask_b32_e64 v144, 0, v140, s[38:39]
	v_cndmask_b32_e64 v145, 0, v141, s[38:39]
	v_cndmask_b32_e64 v246, 0, v142, s[38:39]
	v_cndmask_b32_e64 v247, 0, v143, s[38:39]
	v_fmac_f32_dpp v242, v82, v144 row_ror:1 row_mask:0xf bank_mask:0xf
	v_fmac_f32_dpp v243, v83, v145 row_ror:1 row_mask:0xf bank_mask:0xf
	v_fmac_f32_dpp v244, v84, v246 row_ror:1 row_mask:0xf bank_mask:0xf
	v_fmac_f32_dpp v245, v85, v247 row_ror:1 row_mask:0xf bank_mask:0xf
	v_cndmask_b32_e64 v144, 0, v166, s[40:41]
	v_cndmask_b32_e64 v145, 0, v167, s[40:41]
	v_cndmask_b32_e64 v246, 0, v168, s[40:41]
	v_cndmask_b32_e64 v247, 0, v169, s[40:41]
	v_fmac_f32_dpp v238, v66, v144 row_ror:15 row_mask:0xf bank_mask:0xf
	v_fmac_f32_dpp v239, v67, v145 row_ror:15 row_mask:0xf bank_mask:0xf
	v_fmac_f32_dpp v240, v68, v246 row_ror:15 row_mask:0xf bank_mask:0xf
	v_fmac_f32_dpp v241, v69, v247 row_ror:15 row_mask:0xf bank_mask:0xf
	v_cndmask_b32_e64 v144, 0, v170, s[40:41]
	v_cndmask_b32_e64 v145, 0, v171, s[40:41]
	v_cndmask_b32_e64 v246, 0, v172, s[40:41]
	v_cndmask_b32_e64 v247, 0, v173, s[40:41]
	v_fmac_f32_dpp v242, v70, v144 row_ror:15 row_mask:0xf bank_mask:0xf
	v_fmac_f32_dpp v243, v71, v145 row_ror:15 row_mask:0xf bank_mask:0xf
	v_fmac_f32_dpp v244, v72, v246 row_ror:15 row_mask:0xf bank_mask:0xf
	v_fmac_f32_dpp v245, v73, v247 row_ror:15 row_mask:0xf bank_mask:0xf
	v_pk_mul_f32 v[144:145], v[242:243], s[6:7] op_sel_hi:[1,0]
	v_pk_mul_f32 v[246:247], v[244:245], s[6:7] op_sel_hi:[1,0]
	v_exp_f32_e32 v144, v144
	v_exp_f32_e32 v145, v145
	v_exp_f32_e32 v246, v246
	v_exp_f32_e32 v247, v247
	v_add_f32_e32 v144, 1.0, v144
	v_add_f32_e32 v145, 1.0, v145
	v_add_f32_e32 v246, 1.0, v246
	v_add_f32_e32 v247, 1.0, v247
	v_rcp_f32_e32 v144, v144
	v_rcp_f32_e32 v145, v145
	v_rcp_f32_e32 v246, v246
	v_rcp_f32_e32 v247, v247
	s_nop 0
	v_pk_mul_f32 v[144:145], v[242:243], v[144:145]
	v_pk_mul_f32 v[246:247], v[244:245], v[246:247]
	v_pk_mul_f32 v[144:145], v[238:239], v[144:145]
	v_pk_mul_f32 v[246:247], v[240:241], v[246:247]
	v_cvt_pk_bf16_f32 v130, v144, v145
	v_cvt_pk_bf16_f32 v131, v246, v247
	v_pk_fma_f32 v[238:239], v[150:151], v[66:67], v[174:175]
	v_pk_fma_f32 v[240:241], v[152:153], v[68:69], v[176:177]
	v_pk_fma_f32 v[242:243], v[162:163], v[70:71], v[188:189]
	v_pk_fma_f32 v[244:245], v[164:165], v[72:73], v[190:191]
	v_fmac_f32_dpp v238, v66, v136 row_shr:1 row_mask:0xf bank_mask:0xf
	v_fmac_f32_dpp v239, v67, v137 row_shr:1 row_mask:0xf bank_mask:0xf
	v_fmac_f32_dpp v240, v68, v138 row_shr:1 row_mask:0xf bank_mask:0xf
	v_fmac_f32_dpp v241, v69, v139 row_shr:1 row_mask:0xf bank_mask:0xf
	v_fmac_f32_dpp v242, v70, v140 row_shr:1 row_mask:0xf bank_mask:0xf
	v_fmac_f32_dpp v243, v71, v141 row_shr:1 row_mask:0xf bank_mask:0xf
	v_fmac_f32_dpp v244, v72, v142 row_shr:1 row_mask:0xf bank_mask:0xf
	v_fmac_f32_dpp v245, v73, v143 row_shr:1 row_mask:0xf bank_mask:0xf
	v_fmac_f32_dpp v238, v66, v166 row_shl:1 row_mask:0xf bank_mask:0xf
	v_fmac_f32_dpp v239, v67, v167 row_shl:1 row_mask:0xf bank_mask:0xf
	v_fmac_f32_dpp v240, v68, v168 row_shl:1 row_mask:0xf bank_mask:0xf
	v_fmac_f32_dpp v241, v69, v169 row_shl:1 row_mask:0xf bank_mask:0xf
	v_fmac_f32_dpp v242, v70, v170 row_shl:1 row_mask:0xf bank_mask:0xf
	v_fmac_f32_dpp v243, v71, v171 row_shl:1 row_mask:0xf bank_mask:0xf
	v_fmac_f32_dpp v244, v72, v172 row_shl:1 row_mask:0xf bank_mask:0xf
	v_fmac_f32_dpp v245, v73, v173 row_shl:1 row_mask:0xf bank_mask:0xf
	v_cndmask_b32_e64 v144, 0, v136, s[38:39]
	v_cndmask_b32_e64 v145, 0, v137, s[38:39]
	v_cndmask_b32_e64 v246, 0, v138, s[38:39]
	v_cndmask_b32_e64 v247, 0, v139, s[38:39]
	v_fmac_f32_dpp v238, v78, v144 row_ror:1 row_mask:0xf bank_mask:0xf
	v_fmac_f32_dpp v239, v79, v145 row_ror:1 row_mask:0xf bank_mask:0xf
	v_fmac_f32_dpp v240, v80, v246 row_ror:1 row_mask:0xf bank_mask:0xf
	v_fmac_f32_dpp v241, v81, v247 row_ror:1 row_mask:0xf bank_mask:0xf
	v_cndmask_b32_e64 v144, 0, v140, s[38:39]
	v_cndmask_b32_e64 v145, 0, v141, s[38:39]
	v_cndmask_b32_e64 v246, 0, v142, s[38:39]
	v_cndmask_b32_e64 v247, 0, v143, s[38:39]
	v_fmac_f32_dpp v242, v74, v144 row_ror:1 row_mask:0xf bank_mask:0xf
	v_fmac_f32_dpp v243, v75, v145 row_ror:1 row_mask:0xf bank_mask:0xf
	v_fmac_f32_dpp v244, v76, v246 row_ror:1 row_mask:0xf bank_mask:0xf
	v_fmac_f32_dpp v245, v77, v247 row_ror:1 row_mask:0xf bank_mask:0xf
	s_waitcnt lgkmcnt(0)
	s_cmp_eq_u32 s4, 64
	s_cbranch_scc1 .Lupc_3
	v_cndmask_b32_e64 v144, 0, v166, s[40:41]
	v_cndmask_b32_e64 v145, 0, v167, s[40:41]
	v_cndmask_b32_e64 v246, 0, v168, s[40:41]
	v_cndmask_b32_e64 v247, 0, v169, s[40:41]
	v_pk_fma_f32 v[238:239], v[192:193], v[144:145], v[238:239]
	v_pk_fma_f32 v[240:241], v[194:195], v[246:247], v[240:241]
	v_cndmask_b32_e64 v144, 0, v170, s[40:41]
	v_cndmask_b32_e64 v145, 0, v171, s[40:41]
	v_cndmask_b32_e64 v246, 0, v172, s[40:41]
	v_cndmask_b32_e64 v247, 0, v173, s[40:41]
	v_pk_fma_f32 v[242:243], v[212:213], v[144:145], v[242:243]
	v_pk_fma_f32 v[244:245], v[214:215], v[246:247], v[244:245]
.Lupc_3:
	s_cmp_lg_u32 s4, 64
	s_cbranch_scc1 .Lupc_4
	s_mov_b64 exec, s[40:41]
	s_lshl_b32 s7, s72, 1
	s_or_b32 s7, s7, 1
	s_mul_i32 s7, s7, 0xb000
	v_readlane_b32 s26, v255, 0
	v_readlane_b32 s27, v255, 1
	s_add_u32 s26, s26, s7
	s_addc_u32 s27, s27, 0
	global_store_dwordx4 v196, v[66:69], s[26:27] offset:0
	s_add_u32 s26, s26, 22528
	s_addc_u32 s27, s27, 0
	global_store_dwordx4 v196, v[70:73], s[26:27] offset:0
	v_readlane_b32 s26, v255, 15
	v_readlane_b32 s27, v255, 16
	s_add_u32 s26, s26, s7
	s_addc_u32 s27, s27, 0
	global_store_dwordx4 v196, v[238:241], s[26:27] offset:0
	s_add_u32 s26, s26, 22528
	s_addc_u32 s27, s27, 0
	global_store_dwordx4 v196, v[242:245], s[26:27] offset:0
	s_mov_b64 exec, -1
.Lupc_4:
	v_pk_mul_f32 v[144:145], v[242:243], s[6:7] op_sel_hi:[1,0]
	v_pk_mul_f32 v[246:247], v[244:245], s[6:7] op_sel_hi:[1,0]
	v_exp_f32_e32 v144, v144
	v_exp_f32_e32 v145, v145
	v_exp_f32_e32 v246, v246
	v_exp_f32_e32 v247, v247
	v_add_f32_e32 v144, 1.0, v144
	v_add_f32_e32 v145, 1.0, v145
	v_add_f32_e32 v246, 1.0, v246
	v_add_f32_e32 v247, 1.0, v247
	v_rcp_f32_e32 v144, v144
	v_rcp_f32_e32 v145, v145
	v_rcp_f32_e32 v246, v246
	v_rcp_f32_e32 v247, v247
	s_nop 0
	v_pk_mul_f32 v[144:145], v[242:243], v[144:145]
	v_pk_mul_f32 v[246:247], v[244:245], v[246:247]
	v_pk_mul_f32 v[144:145], v[238:239], v[144:145]
	v_pk_mul_f32 v[246:247], v[240:241], v[246:247]
	v_cvt_pk_bf16_f32 v132, v144, v145
	v_cvt_pk_bf16_f32 v133, v246, v247
	ds_read_b128 v[192:195], v197 offset:4112
	ds_read_b128 v[212:215], v197 offset:4624
	s_waitcnt vmcnt(0)
	v_pk_fma_f32 v[238:239], v[146:147], v[2:3], v[102:103]
	v_pk_fma_f32 v[240:241], v[148:149], v[4:5], v[104:105]
	v_pk_fma_f32 v[242:243], v[114:115], v[6:7], v[98:99]
	v_pk_fma_f32 v[244:245], v[116:117], v[8:9], v[100:101]
	v_fmac_f32_dpp v238, v2, v158 row_shr:1 row_mask:0xf bank_mask:0xf
	v_fmac_f32_dpp v239, v3, v159 row_shr:1 row_mask:0xf bank_mask:0xf
	v_fmac_f32_dpp v240, v4, v160 row_shr:1 row_mask:0xf bank_mask:0xf
	v_fmac_f32_dpp v241, v5, v161 row_shr:1 row_mask:0xf bank_mask:0xf
	v_fmac_f32_dpp v242, v6, v154 row_shr:1 row_mask:0xf bank_mask:0xf
	v_fmac_f32_dpp v243, v7, v155 row_shr:1 row_mask:0xf bank_mask:0xf
	v_fmac_f32_dpp v244, v8, v156 row_shr:1 row_mask:0xf bank_mask:0xf
	v_fmac_f32_dpp v245, v9, v157 row_shr:1 row_mask:0xf bank_mask:0xf
	v_fmac_f32_dpp v238, v2, v110 row_shl:1 row_mask:0xf bank_mask:0xf
	v_fmac_f32_dpp v239, v3, v111 row_shl:1 row_mask:0xf bank_mask:0xf
	v_fmac_f32_dpp v240, v4, v112 row_shl:1 row_mask:0xf bank_mask:0xf
	v_fmac_f32_dpp v241, v5, v113 row_shl:1 row_mask:0xf bank_mask:0xf
	v_fmac_f32_dpp v242, v6, v106 row_shl:1 row_mask:0xf bank_mask:0xf
	v_fmac_f32_dpp v243, v7, v107 row_shl:1 row_mask:0xf bank_mask:0xf
	v_fmac_f32_dpp v244, v8, v108 row_shl:1 row_mask:0xf bank_mask:0xf
	v_fmac_f32_dpp v245, v9, v109 row_shl:1 row_mask:0xf bank_mask:0xf
	v_cndmask_b32_e64 v144, 0, v158, s[38:39]
	v_cndmask_b32_e64 v145, 0, v159, s[38:39]
	v_cndmask_b32_e64 v246, 0, v160, s[38:39]
	v_cndmask_b32_e64 v247, 0, v161, s[38:39]
	v_fmac_f32_dpp v238, v14, v144 row_ror:1 row_mask:0xf bank_mask:0xf
	v_fmac_f32_dpp v239, v15, v145 row_ror:1 row_mask:0xf bank_mask:0xf
	v_fmac_f32_dpp v240, v16, v246 row_ror:1 row_mask:0xf bank_mask:0xf
	v_fmac_f32_dpp v241, v17, v247 row_ror:1 row_mask:0xf bank_mask:0xf
	v_cndmask_b32_e64 v144, 0, v154, s[38:39]
	v_cndmask_b32_e64 v145, 0, v155, s[38:39]
	v_cndmask_b32_e64 v246, 0, v156, s[38:39]
	v_cndmask_b32_e64 v247, 0, v157, s[38:39]
	v_fmac_f32_dpp v242, v10, v144 row_ror:1 row_mask:0xf bank_mask:0xf
	v_fmac_f32_dpp v243, v11, v145 row_ror:1 row_mask:0xf bank_mask:0xf
	v_fmac_f32_dpp v244, v12, v246 row_ror:1 row_mask:0xf bank_mask:0xf
	v_fmac_f32_dpp v245, v13, v247 row_ror:1 row_mask:0xf bank_mask:0xf
	s_waitcnt lgkmcnt(0)
	s_cmp_eq_u32 s4, 64
	s_cbranch_scc1 .Lupc_5
	v_cndmask_b32_e64 v144, 0, v110, s[40:41]
	v_cndmask_b32_e64 v145, 0, v111, s[40:41]
	v_cndmask_b32_e64 v246, 0, v112, s[40:41]
	v_cndmask_b32_e64 v247, 0, v113, s[40:41]
	v_pk_fma_f32 v[238:239], v[192:193], v[144:145], v[238:239]
	v_pk_fma_f32 v[240:241], v[194:195], v[246:247], v[240:241]
	v_cndmask_b32_e64 v144, 0, v106, s[40:41]
	v_cndmask_b32_e64 v145, 0, v107, s[40:41]
	v_cndmask_b32_e64 v246, 0, v108, s[40:41]
	v_cndmask_b32_e64 v247, 0, v109, s[40:41]
	v_pk_fma_f32 v[242:243], v[212:213], v[144:145], v[242:243]
	v_pk_fma_f32 v[244:245], v[214:215], v[246:247], v[244:245]
.Lupc_5:
	s_cmp_lg_u32 s4, 64
	s_cbranch_scc1 .Lupc_6
	s_mov_b64 exec, s[40:41]
	s_lshl_b32 s7, s72, 1
	s_or_b32 s7, s7, 1
	s_mul_i32 s7, s7, 0xb000
	v_readlane_b32 s26, v255, 0
	v_readlane_b32 s27, v255, 1
	s_add_u32 s26, s26, s7
	s_addc_u32 s27, s27, 0
	global_store_dwordx4 v196, v[2:5], s[26:27] offset:16
	s_add_u32 s26, s26, 22528
	s_addc_u32 s27, s27, 0
	global_store_dwordx4 v196, v[6:9], s[26:27] offset:16
	v_readlane_b32 s26, v255, 15
	v_readlane_b32 s27, v255, 16
	s_add_u32 s26, s26, s7
	s_addc_u32 s27, s27, 0
	global_store_dwordx4 v196, v[238:241], s[26:27] offset:16
	s_add_u32 s26, s26, 22528
	s_addc_u32 s27, s27, 0
	global_store_dwordx4 v196, v[242:245], s[26:27] offset:16
	s_mov_b64 exec, -1
.Lupc_6:
	v_pk_mul_f32 v[144:145], v[242:243], s[6:7] op_sel_hi:[1,0]
	v_pk_mul_f32 v[246:247], v[244:245], s[6:7] op_sel_hi:[1,0]
	v_exp_f32_e32 v144, v144
	v_exp_f32_e32 v145, v145
	v_exp_f32_e32 v246, v246
	v_exp_f32_e32 v247, v247
	v_add_f32_e32 v144, 1.0, v144
	v_add_f32_e32 v145, 1.0, v145
	v_add_f32_e32 v246, 1.0, v246
	v_add_f32_e32 v247, 1.0, v247
	v_rcp_f32_e32 v144, v144
	v_rcp_f32_e32 v145, v145
	v_rcp_f32_e32 v246, v246
	v_rcp_f32_e32 v247, v247
	s_nop 0
	v_pk_mul_f32 v[144:145], v[242:243], v[144:145]
	v_pk_mul_f32 v[246:247], v[244:245], v[246:247]
	v_pk_mul_f32 v[144:145], v[238:239], v[144:145]
	v_pk_mul_f32 v[246:247], v[240:241], v[246:247]
	v_cvt_pk_bf16_f32 v134, v144, v145
	v_cvt_pk_bf16_f32 v135, v246, v247
	s_add_u32 s26, s94, 0x1e4000
	s_addc_u32 s27, s95, 0
	global_store_dwordx4 v217, v[132:135], s[26:27]
	v_pk_fma_f32 v[238:239], v[146:147], v[14:15], v[102:103]
	v_pk_fma_f32 v[240:241], v[148:149], v[16:17], v[104:105]
	v_pk_fma_f32 v[242:243], v[114:115], v[10:11], v[98:99]
	v_pk_fma_f32 v[244:245], v[116:117], v[12:13], v[100:101]
	v_fmac_f32_dpp v238, v14, v158 row_shr:1 row_mask:0xf bank_mask:0xf
	v_fmac_f32_dpp v239, v15, v159 row_shr:1 row_mask:0xf bank_mask:0xf
	v_fmac_f32_dpp v240, v16, v160 row_shr:1 row_mask:0xf bank_mask:0xf
	v_fmac_f32_dpp v241, v17, v161 row_shr:1 row_mask:0xf bank_mask:0xf
	v_fmac_f32_dpp v242, v10, v154 row_shr:1 row_mask:0xf bank_mask:0xf
	v_fmac_f32_dpp v243, v11, v155 row_shr:1 row_mask:0xf bank_mask:0xf
	v_fmac_f32_dpp v244, v12, v156 row_shr:1 row_mask:0xf bank_mask:0xf
	v_fmac_f32_dpp v245, v13, v157 row_shr:1 row_mask:0xf bank_mask:0xf
	v_fmac_f32_dpp v238, v14, v110 row_shl:1 row_mask:0xf bank_mask:0xf
	v_fmac_f32_dpp v239, v15, v111 row_shl:1 row_mask:0xf bank_mask:0xf
	v_fmac_f32_dpp v240, v16, v112 row_shl:1 row_mask:0xf bank_mask:0xf
	v_fmac_f32_dpp v241, v17, v113 row_shl:1 row_mask:0xf bank_mask:0xf
	v_fmac_f32_dpp v242, v10, v106 row_shl:1 row_mask:0xf bank_mask:0xf
	v_fmac_f32_dpp v243, v11, v107 row_shl:1 row_mask:0xf bank_mask:0xf
	v_fmac_f32_dpp v244, v12, v108 row_shl:1 row_mask:0xf bank_mask:0xf
	v_fmac_f32_dpp v245, v13, v109 row_shl:1 row_mask:0xf bank_mask:0xf
	v_cndmask_b32_e64 v144, 0, v158, s[38:39]
	v_cndmask_b32_e64 v145, 0, v159, s[38:39]
	v_cndmask_b32_e64 v246, 0, v160, s[38:39]
	v_cndmask_b32_e64 v247, 0, v161, s[38:39]
	v_fmac_f32_dpp v238, v22, v144 row_ror:1 row_mask:0xf bank_mask:0xf
	v_fmac_f32_dpp v239, v23, v145 row_ror:1 row_mask:0xf bank_mask:0xf
	v_fmac_f32_dpp v240, v24, v246 row_ror:1 row_mask:0xf bank_mask:0xf
	v_fmac_f32_dpp v241, v25, v247 row_ror:1 row_mask:0xf bank_mask:0xf
	v_cndmask_b32_e64 v144, 0, v154, s[38:39]
	v_cndmask_b32_e64 v145, 0, v155, s[38:39]
	v_cndmask_b32_e64 v246, 0, v156, s[38:39]
	v_cndmask_b32_e64 v247, 0, v157, s[38:39]
	v_fmac_f32_dpp v242, v18, v144 row_ror:1 row_mask:0xf bank_mask:0xf
	v_fmac_f32_dpp v243, v19, v145 row_ror:1 row_mask:0xf bank_mask:0xf
	v_fmac_f32_dpp v244, v20, v246 row_ror:1 row_mask:0xf bank_mask:0xf
	v_fmac_f32_dpp v245, v21, v247 row_ror:1 row_mask:0xf bank_mask:0xf
	v_cndmask_b32_e64 v144, 0, v110, s[40:41]
	v_cndmask_b32_e64 v145, 0, v111, s[40:41]
	v_cndmask_b32_e64 v246, 0, v112, s[40:41]
	v_cndmask_b32_e64 v247, 0, v113, s[40:41]
	v_fmac_f32_dpp v238, v2, v144 row_ror:15 row_mask:0xf bank_mask:0xf
	v_fmac_f32_dpp v239, v3, v145 row_ror:15 row_mask:0xf bank_mask:0xf
	v_fmac_f32_dpp v240, v4, v246 row_ror:15 row_mask:0xf bank_mask:0xf
	v_fmac_f32_dpp v241, v5, v247 row_ror:15 row_mask:0xf bank_mask:0xf
	v_cndmask_b32_e64 v144, 0, v106, s[40:41]
	v_cndmask_b32_e64 v145, 0, v107, s[40:41]
	v_cndmask_b32_e64 v246, 0, v108, s[40:41]
	v_cndmask_b32_e64 v247, 0, v109, s[40:41]
	v_fmac_f32_dpp v242, v6, v144 row_ror:15 row_mask:0xf bank_mask:0xf
	v_fmac_f32_dpp v243, v7, v145 row_ror:15 row_mask:0xf bank_mask:0xf
	v_fmac_f32_dpp v244, v8, v246 row_ror:15 row_mask:0xf bank_mask:0xf
	v_fmac_f32_dpp v245, v9, v247 row_ror:15 row_mask:0xf bank_mask:0xf
	v_pk_mul_f32 v[144:145], v[242:243], s[6:7] op_sel_hi:[1,0]
	v_pk_mul_f32 v[246:247], v[244:245], s[6:7] op_sel_hi:[1,0]
	v_exp_f32_e32 v144, v144
	v_exp_f32_e32 v145, v145
	v_exp_f32_e32 v246, v246
	v_exp_f32_e32 v247, v247
	v_add_f32_e32 v144, 1.0, v144
	v_add_f32_e32 v145, 1.0, v145
	v_add_f32_e32 v246, 1.0, v246
	v_add_f32_e32 v247, 1.0, v247
	v_rcp_f32_e32 v144, v144
	v_rcp_f32_e32 v145, v145
	v_rcp_f32_e32 v246, v246
	v_rcp_f32_e32 v247, v247
	s_nop 0
	v_pk_mul_f32 v[144:145], v[242:243], v[144:145]
	v_pk_mul_f32 v[246:247], v[244:245], v[246:247]
	v_pk_mul_f32 v[144:145], v[238:239], v[144:145]
	v_pk_mul_f32 v[246:247], v[240:241], v[246:247]
	v_cvt_pk_bf16_f32 v132, v144, v145
	v_cvt_pk_bf16_f32 v133, v246, v247
	s_add_u32 s26, s94, 0x1b8000
	s_addc_u32 s27, s95, 0
	global_store_dwordx4 v217, v[130:133], s[26:27]
	v_pk_fma_f32 v[238:239], v[146:147], v[22:23], v[102:103]
	v_pk_fma_f32 v[240:241], v[148:149], v[24:25], v[104:105]
	v_pk_fma_f32 v[242:243], v[114:115], v[18:19], v[98:99]
	v_pk_fma_f32 v[244:245], v[116:117], v[20:21], v[100:101]
	v_fmac_f32_dpp v238, v22, v158 row_shr:1 row_mask:0xf bank_mask:0xf
	v_fmac_f32_dpp v239, v23, v159 row_shr:1 row_mask:0xf bank_mask:0xf
	v_fmac_f32_dpp v240, v24, v160 row_shr:1 row_mask:0xf bank_mask:0xf
	v_fmac_f32_dpp v241, v25, v161 row_shr:1 row_mask:0xf bank_mask:0xf
	v_fmac_f32_dpp v242, v18, v154 row_shr:1 row_mask:0xf bank_mask:0xf
	v_fmac_f32_dpp v243, v19, v155 row_shr:1 row_mask:0xf bank_mask:0xf
	v_fmac_f32_dpp v244, v20, v156 row_shr:1 row_mask:0xf bank_mask:0xf
	v_fmac_f32_dpp v245, v21, v157 row_shr:1 row_mask:0xf bank_mask:0xf
	v_fmac_f32_dpp v238, v22, v110 row_shl:1 row_mask:0xf bank_mask:0xf
	v_fmac_f32_dpp v239, v23, v111 row_shl:1 row_mask:0xf bank_mask:0xf
	v_fmac_f32_dpp v240, v24, v112 row_shl:1 row_mask:0xf bank_mask:0xf
	v_fmac_f32_dpp v241, v25, v113 row_shl:1 row_mask:0xf bank_mask:0xf
	v_fmac_f32_dpp v242, v18, v106 row_shl:1 row_mask:0xf bank_mask:0xf
	v_fmac_f32_dpp v243, v19, v107 row_shl:1 row_mask:0xf bank_mask:0xf
	v_fmac_f32_dpp v244, v20, v108 row_shl:1 row_mask:0xf bank_mask:0xf
	v_fmac_f32_dpp v245, v21, v109 row_shl:1 row_mask:0xf bank_mask:0xf
	v_cndmask_b32_e64 v144, 0, v158, s[38:39]
	v_cndmask_b32_e64 v145, 0, v159, s[38:39]
	v_cndmask_b32_e64 v246, 0, v160, s[38:39]
	v_cndmask_b32_e64 v247, 0, v161, s[38:39]
	v_fmac_f32_dpp v238, v30, v144 row_ror:1 row_mask:0xf bank_mask:0xf
	v_fmac_f32_dpp v239, v31, v145 row_ror:1 row_mask:0xf bank_mask:0xf
	v_fmac_f32_dpp v240, v32, v246 row_ror:1 row_mask:0xf bank_mask:0xf
	v_fmac_f32_dpp v241, v33, v247 row_ror:1 row_mask:0xf bank_mask:0xf
	v_cndmask_b32_e64 v144, 0, v154, s[38:39]
	v_cndmask_b32_e64 v145, 0, v155, s[38:39]
	v_cndmask_b32_e64 v246, 0, v156, s[38:39]
	v_cndmask_b32_e64 v247, 0, v157, s[38:39]
	v_fmac_f32_dpp v242, v26, v144 row_ror:1 row_mask:0xf bank_mask:0xf
	v_fmac_f32_dpp v243, v27, v145 row_ror:1 row_mask:0xf bank_mask:0xf
	v_fmac_f32_dpp v244, v28, v246 row_ror:1 row_mask:0xf bank_mask:0xf
	v_fmac_f32_dpp v245, v29, v247 row_ror:1 row_mask:0xf bank_mask:0xf
	v_cndmask_b32_e64 v144, 0, v110, s[40:41]
	v_cndmask_b32_e64 v145, 0, v111, s[40:41]
	v_cndmask_b32_e64 v246, 0, v112, s[40:41]
	v_cndmask_b32_e64 v247, 0, v113, s[40:41]
	v_fmac_f32_dpp v238, v14, v144 row_ror:15 row_mask:0xf bank_mask:0xf
	v_fmac_f32_dpp v239, v15, v145 row_ror:15 row_mask:0xf bank_mask:0xf
	v_fmac_f32_dpp v240, v16, v246 row_ror:15 row_mask:0xf bank_mask:0xf
	v_fmac_f32_dpp v241, v17, v247 row_ror:15 row_mask:0xf bank_mask:0xf
	v_cndmask_b32_e64 v144, 0, v106, s[40:41]
	v_cndmask_b32_e64 v145, 0, v107, s[40:41]
	v_cndmask_b32_e64 v246, 0, v108, s[40:41]
	v_cndmask_b32_e64 v247, 0, v109, s[40:41]
	v_fmac_f32_dpp v242, v10, v144 row_ror:15 row_mask:0xf bank_mask:0xf
	v_fmac_f32_dpp v243, v11, v145 row_ror:15 row_mask:0xf bank_mask:0xf
	v_fmac_f32_dpp v244, v12, v246 row_ror:15 row_mask:0xf bank_mask:0xf
	v_fmac_f32_dpp v245, v13, v247 row_ror:15 row_mask:0xf bank_mask:0xf
	v_pk_mul_f32 v[144:145], v[242:243], s[6:7] op_sel_hi:[1,0]
	v_pk_mul_f32 v[246:247], v[244:245], s[6:7] op_sel_hi:[1,0]
	v_exp_f32_e32 v144, v144
	v_exp_f32_e32 v145, v145
	v_exp_f32_e32 v246, v246
	v_exp_f32_e32 v247, v247
	v_add_f32_e32 v144, 1.0, v144
	v_add_f32_e32 v145, 1.0, v145
	v_add_f32_e32 v246, 1.0, v246
	v_add_f32_e32 v247, 1.0, v247
	v_rcp_f32_e32 v144, v144
	v_rcp_f32_e32 v145, v145
	v_rcp_f32_e32 v246, v246
	v_rcp_f32_e32 v247, v247
	s_nop 0
	v_pk_mul_f32 v[144:145], v[242:243], v[144:145]
	v_pk_mul_f32 v[246:247], v[244:245], v[246:247]
	v_pk_mul_f32 v[144:145], v[238:239], v[144:145]
	v_pk_mul_f32 v[246:247], v[240:241], v[246:247]
	v_cvt_pk_bf16_f32 v130, v144, v145
	v_cvt_pk_bf16_f32 v131, v246, v247
	s_add_u32 s26, s94, 0x18c000
	s_addc_u32 s27, s95, 0
	global_store_dwordx4 v217, v[128:131], s[26:27]
	v_pk_fma_f32 v[238:239], v[146:147], v[30:31], v[102:103]
	v_pk_fma_f32 v[240:241], v[148:149], v[32:33], v[104:105]
	v_pk_fma_f32 v[242:243], v[114:115], v[26:27], v[98:99]
	v_pk_fma_f32 v[244:245], v[116:117], v[28:29], v[100:101]
	v_fmac_f32_dpp v238, v30, v158 row_shr:1 row_mask:0xf bank_mask:0xf
	v_fmac_f32_dpp v239, v31, v159 row_shr:1 row_mask:0xf bank_mask:0xf
	v_fmac_f32_dpp v240, v32, v160 row_shr:1 row_mask:0xf bank_mask:0xf
	v_fmac_f32_dpp v241, v33, v161 row_shr:1 row_mask:0xf bank_mask:0xf
	v_fmac_f32_dpp v242, v26, v154 row_shr:1 row_mask:0xf bank_mask:0xf
	v_fmac_f32_dpp v243, v27, v155 row_shr:1 row_mask:0xf bank_mask:0xf
	v_fmac_f32_dpp v244, v28, v156 row_shr:1 row_mask:0xf bank_mask:0xf
	v_fmac_f32_dpp v245, v29, v157 row_shr:1 row_mask:0xf bank_mask:0xf
	v_fmac_f32_dpp v238, v30, v110 row_shl:1 row_mask:0xf bank_mask:0xf
	v_fmac_f32_dpp v239, v31, v111 row_shl:1 row_mask:0xf bank_mask:0xf
	v_fmac_f32_dpp v240, v32, v112 row_shl:1 row_mask:0xf bank_mask:0xf
	v_fmac_f32_dpp v241, v33, v113 row_shl:1 row_mask:0xf bank_mask:0xf
	v_fmac_f32_dpp v242, v26, v106 row_shl:1 row_mask:0xf bank_mask:0xf
	v_fmac_f32_dpp v243, v27, v107 row_shl:1 row_mask:0xf bank_mask:0xf
	v_fmac_f32_dpp v244, v28, v108 row_shl:1 row_mask:0xf bank_mask:0xf
	v_fmac_f32_dpp v245, v29, v109 row_shl:1 row_mask:0xf bank_mask:0xf
	s_waitcnt lgkmcnt(0)
	v_cndmask_b32_e64 v144, 0, v158, s[38:39]
	v_cndmask_b32_e64 v145, 0, v159, s[38:39]
	v_cndmask_b32_e64 v246, 0, v160, s[38:39]
	v_cndmask_b32_e64 v247, 0, v161, s[38:39]
	v_pk_fma_f32 v[238:239], v[192:193], v[144:145], v[238:239]
	v_pk_fma_f32 v[240:241], v[194:195], v[246:247], v[240:241]
	v_cndmask_b32_e64 v144, 0, v154, s[38:39]
	v_cndmask_b32_e64 v145, 0, v155, s[38:39]
	v_cndmask_b32_e64 v246, 0, v156, s[38:39]
	v_cndmask_b32_e64 v247, 0, v157, s[38:39]
	v_pk_fma_f32 v[242:243], v[212:213], v[144:145], v[242:243]
	v_pk_fma_f32 v[244:245], v[214:215], v[246:247], v[244:245]
	v_cndmask_b32_e64 v144, 0, v110, s[40:41]
	v_cndmask_b32_e64 v145, 0, v111, s[40:41]
	v_cndmask_b32_e64 v246, 0, v112, s[40:41]
	v_cndmask_b32_e64 v247, 0, v113, s[40:41]
	v_fmac_f32_dpp v238, v22, v144 row_ror:15 row_mask:0xf bank_mask:0xf
	v_fmac_f32_dpp v239, v23, v145 row_ror:15 row_mask:0xf bank_mask:0xf
	v_fmac_f32_dpp v240, v24, v246 row_ror:15 row_mask:0xf bank_mask:0xf
	v_fmac_f32_dpp v241, v25, v247 row_ror:15 row_mask:0xf bank_mask:0xf
	v_cndmask_b32_e64 v144, 0, v106, s[40:41]
	v_cndmask_b32_e64 v145, 0, v107, s[40:41]
	v_cndmask_b32_e64 v246, 0, v108, s[40:41]
	v_cndmask_b32_e64 v247, 0, v109, s[40:41]
	v_fmac_f32_dpp v242, v18, v144 row_ror:15 row_mask:0xf bank_mask:0xf
	v_fmac_f32_dpp v243, v19, v145 row_ror:15 row_mask:0xf bank_mask:0xf
	v_fmac_f32_dpp v244, v20, v246 row_ror:15 row_mask:0xf bank_mask:0xf
	v_fmac_f32_dpp v245, v21, v247 row_ror:15 row_mask:0xf bank_mask:0xf
	v_pk_mul_f32 v[144:145], v[242:243], s[6:7] op_sel_hi:[1,0]
	v_pk_mul_f32 v[246:247], v[244:245], s[6:7] op_sel_hi:[1,0]
	v_exp_f32_e32 v144, v144
	v_exp_f32_e32 v145, v145
	v_exp_f32_e32 v246, v246
	v_exp_f32_e32 v247, v247
	v_add_f32_e32 v144, 1.0, v144
	v_add_f32_e32 v145, 1.0, v145
	v_add_f32_e32 v246, 1.0, v246
	v_add_f32_e32 v247, 1.0, v247
	v_rcp_f32_e32 v144, v144
	v_rcp_f32_e32 v145, v145
	v_rcp_f32_e32 v246, v246
	v_rcp_f32_e32 v247, v247
	s_nop 0
	v_pk_mul_f32 v[144:145], v[242:243], v[144:145]
	v_pk_mul_f32 v[246:247], v[244:245], v[246:247]
	v_pk_mul_f32 v[144:145], v[238:239], v[144:145]
	v_pk_mul_f32 v[246:247], v[240:241], v[246:247]
	v_cvt_pk_bf16_f32 v128, v144, v145
	v_cvt_pk_bf16_f32 v129, v246, v247
	s_add_u32 s26, s94, 0x160000
	s_addc_u32 s27, s95, 0
	global_store_dwordx4 v217, v[126:129], s[26:27]
	ds_read_b128 v[192:195], v216 offset:16
	ds_read_b128 v[212:215], v216 offset:528
	v_pk_fma_f32 v[238:239], v[146:147], v[38:39], v[102:103]
	v_pk_fma_f32 v[240:241], v[148:149], v[40:41], v[104:105]
	v_pk_fma_f32 v[242:243], v[114:115], v[34:35], v[98:99]
	v_pk_fma_f32 v[244:245], v[116:117], v[36:37], v[100:101]
	v_fmac_f32_dpp v238, v38, v158 row_shr:1 row_mask:0xf bank_mask:0xf
	v_fmac_f32_dpp v239, v39, v159 row_shr:1 row_mask:0xf bank_mask:0xf
	v_fmac_f32_dpp v240, v40, v160 row_shr:1 row_mask:0xf bank_mask:0xf
	v_fmac_f32_dpp v241, v41, v161 row_shr:1 row_mask:0xf bank_mask:0xf
	v_fmac_f32_dpp v242, v34, v154 row_shr:1 row_mask:0xf bank_mask:0xf
	v_fmac_f32_dpp v243, v35, v155 row_shr:1 row_mask:0xf bank_mask:0xf
	v_fmac_f32_dpp v244, v36, v156 row_shr:1 row_mask:0xf bank_mask:0xf
	v_fmac_f32_dpp v245, v37, v157 row_shr:1 row_mask:0xf bank_mask:0xf
	v_fmac_f32_dpp v238, v38, v110 row_shl:1 row_mask:0xf bank_mask:0xf
	v_fmac_f32_dpp v239, v39, v111 row_shl:1 row_mask:0xf bank_mask:0xf
	v_fmac_f32_dpp v240, v40, v112 row_shl:1 row_mask:0xf bank_mask:0xf
	v_fmac_f32_dpp v241, v41, v113 row_shl:1 row_mask:0xf bank_mask:0xf
	v_fmac_f32_dpp v242, v34, v106 row_shl:1 row_mask:0xf bank_mask:0xf
	v_fmac_f32_dpp v243, v35, v107 row_shl:1 row_mask:0xf bank_mask:0xf
	v_fmac_f32_dpp v244, v36, v108 row_shl:1 row_mask:0xf bank_mask:0xf
	v_fmac_f32_dpp v245, v37, v109 row_shl:1 row_mask:0xf bank_mask:0xf
	v_cndmask_b32_e64 v144, 0, v158, s[38:39]
	v_cndmask_b32_e64 v145, 0, v159, s[38:39]
	v_cndmask_b32_e64 v246, 0, v160, s[38:39]
	v_cndmask_b32_e64 v247, 0, v161, s[38:39]
	v_fmac_f32_dpp v238, v46, v144 row_ror:1 row_mask:0xf bank_mask:0xf
	v_fmac_f32_dpp v239, v47, v145 row_ror:1 row_mask:0xf bank_mask:0xf
	v_fmac_f32_dpp v240, v48, v246 row_ror:1 row_mask:0xf bank_mask:0xf
	v_fmac_f32_dpp v241, v49, v247 row_ror:1 row_mask:0xf bank_mask:0xf
	v_cndmask_b32_e64 v144, 0, v154, s[38:39]
	v_cndmask_b32_e64 v145, 0, v155, s[38:39]
	v_cndmask_b32_e64 v246, 0, v156, s[38:39]
	v_cndmask_b32_e64 v247, 0, v157, s[38:39]
	v_fmac_f32_dpp v242, v42, v144 row_ror:1 row_mask:0xf bank_mask:0xf
	v_fmac_f32_dpp v243, v43, v145 row_ror:1 row_mask:0xf bank_mask:0xf
	v_fmac_f32_dpp v244, v44, v246 row_ror:1 row_mask:0xf bank_mask:0xf
	v_fmac_f32_dpp v245, v45, v247 row_ror:1 row_mask:0xf bank_mask:0xf
	s_waitcnt lgkmcnt(0)
	v_cndmask_b32_e64 v144, 0, v110, s[40:41]
	v_cndmask_b32_e64 v145, 0, v111, s[40:41]
	v_cndmask_b32_e64 v246, 0, v112, s[40:41]
	v_cndmask_b32_e64 v247, 0, v113, s[40:41]
	v_pk_fma_f32 v[238:239], v[192:193], v[144:145], v[238:239]
	v_pk_fma_f32 v[240:241], v[194:195], v[246:247], v[240:241]
	v_cndmask_b32_e64 v144, 0, v106, s[40:41]
	v_cndmask_b32_e64 v145, 0, v107, s[40:41]
	v_cndmask_b32_e64 v246, 0, v108, s[40:41]
	v_cndmask_b32_e64 v247, 0, v109, s[40:41]
	v_pk_fma_f32 v[242:243], v[212:213], v[144:145], v[242:243]
	v_pk_fma_f32 v[244:245], v[214:215], v[246:247], v[244:245]
	v_pk_mul_f32 v[144:145], v[242:243], s[6:7] op_sel_hi:[1,0]
	v_pk_mul_f32 v[246:247], v[244:245], s[6:7] op_sel_hi:[1,0]
	v_exp_f32_e32 v144, v144
	v_exp_f32_e32 v145, v145
	v_exp_f32_e32 v246, v246
	v_exp_f32_e32 v247, v247
	v_add_f32_e32 v144, 1.0, v144
	v_add_f32_e32 v145, 1.0, v145
	v_add_f32_e32 v246, 1.0, v246
	v_add_f32_e32 v247, 1.0, v247
	v_rcp_f32_e32 v144, v144
	v_rcp_f32_e32 v145, v145
	v_rcp_f32_e32 v246, v246
	v_rcp_f32_e32 v247, v247
	s_nop 0
	v_pk_mul_f32 v[144:145], v[242:243], v[144:145]
	v_pk_mul_f32 v[246:247], v[244:245], v[246:247]
	v_pk_mul_f32 v[144:145], v[238:239], v[144:145]
	v_pk_mul_f32 v[246:247], v[240:241], v[246:247]
	v_cvt_pk_bf16_f32 v126, v144, v145
	v_cvt_pk_bf16_f32 v127, v246, v247
	s_add_u32 s26, s94, 0x84000
	s_addc_u32 s27, s95, 0
	global_store_dwordx4 v217, v[124:127], s[26:27]
	v_pk_fma_f32 v[238:239], v[146:147], v[46:47], v[102:103]
	v_pk_fma_f32 v[240:241], v[148:149], v[48:49], v[104:105]
	v_pk_fma_f32 v[242:243], v[114:115], v[42:43], v[98:99]
	v_pk_fma_f32 v[244:245], v[116:117], v[44:45], v[100:101]
	v_fmac_f32_dpp v238, v46, v158 row_shr:1 row_mask:0xf bank_mask:0xf
	v_fmac_f32_dpp v239, v47, v159 row_shr:1 row_mask:0xf bank_mask:0xf
	v_fmac_f32_dpp v240, v48, v160 row_shr:1 row_mask:0xf bank_mask:0xf
	v_fmac_f32_dpp v241, v49, v161 row_shr:1 row_mask:0xf bank_mask:0xf
	v_fmac_f32_dpp v242, v42, v154 row_shr:1 row_mask:0xf bank_mask:0xf
	v_fmac_f32_dpp v243, v43, v155 row_shr:1 row_mask:0xf bank_mask:0xf
	v_fmac_f32_dpp v244, v44, v156 row_shr:1 row_mask:0xf bank_mask:0xf
	v_fmac_f32_dpp v245, v45, v157 row_shr:1 row_mask:0xf bank_mask:0xf
	v_fmac_f32_dpp v238, v46, v110 row_shl:1 row_mask:0xf bank_mask:0xf
	v_fmac_f32_dpp v239, v47, v111 row_shl:1 row_mask:0xf bank_mask:0xf
	v_fmac_f32_dpp v240, v48, v112 row_shl:1 row_mask:0xf bank_mask:0xf
	v_fmac_f32_dpp v241, v49, v113 row_shl:1 row_mask:0xf bank_mask:0xf
	v_fmac_f32_dpp v242, v42, v106 row_shl:1 row_mask:0xf bank_mask:0xf
	v_fmac_f32_dpp v243, v43, v107 row_shl:1 row_mask:0xf bank_mask:0xf
	v_fmac_f32_dpp v244, v44, v108 row_shl:1 row_mask:0xf bank_mask:0xf
	v_fmac_f32_dpp v245, v45, v109 row_shl:1 row_mask:0xf bank_mask:0xf
	v_cndmask_b32_e64 v144, 0, v158, s[38:39]
	v_cndmask_b32_e64 v145, 0, v159, s[38:39]
	v_cndmask_b32_e64 v246, 0, v160, s[38:39]
	v_cndmask_b32_e64 v247, 0, v161, s[38:39]
	v_fmac_f32_dpp v238, v54, v144 row_ror:1 row_mask:0xf bank_mask:0xf
	v_fmac_f32_dpp v239, v55, v145 row_ror:1 row_mask:0xf bank_mask:0xf
	v_fmac_f32_dpp v240, v56, v246 row_ror:1 row_mask:0xf bank_mask:0xf
	v_fmac_f32_dpp v241, v57, v247 row_ror:1 row_mask:0xf bank_mask:0xf
	v_cndmask_b32_e64 v144, 0, v154, s[38:39]
	v_cndmask_b32_e64 v145, 0, v155, s[38:39]
	v_cndmask_b32_e64 v246, 0, v156, s[38:39]
	v_cndmask_b32_e64 v247, 0, v157, s[38:39]
	v_fmac_f32_dpp v242, v50, v144 row_ror:1 row_mask:0xf bank_mask:0xf
	v_fmac_f32_dpp v243, v51, v145 row_ror:1 row_mask:0xf bank_mask:0xf
	v_fmac_f32_dpp v244, v52, v246 row_ror:1 row_mask:0xf bank_mask:0xf
	v_fmac_f32_dpp v245, v53, v247 row_ror:1 row_mask:0xf bank_mask:0xf
	v_cndmask_b32_e64 v144, 0, v110, s[40:41]
	v_cndmask_b32_e64 v145, 0, v111, s[40:41]
	v_cndmask_b32_e64 v246, 0, v112, s[40:41]
	v_cndmask_b32_e64 v247, 0, v113, s[40:41]
	v_fmac_f32_dpp v238, v38, v144 row_ror:15 row_mask:0xf bank_mask:0xf
	v_fmac_f32_dpp v239, v39, v145 row_ror:15 row_mask:0xf bank_mask:0xf
	v_fmac_f32_dpp v240, v40, v246 row_ror:15 row_mask:0xf bank_mask:0xf
	v_fmac_f32_dpp v241, v41, v247 row_ror:15 row_mask:0xf bank_mask:0xf
	v_cndmask_b32_e64 v144, 0, v106, s[40:41]
	v_cndmask_b32_e64 v145, 0, v107, s[40:41]
	v_cndmask_b32_e64 v246, 0, v108, s[40:41]
	v_cndmask_b32_e64 v247, 0, v109, s[40:41]
	v_fmac_f32_dpp v242, v34, v144 row_ror:15 row_mask:0xf bank_mask:0xf
	v_fmac_f32_dpp v243, v35, v145 row_ror:15 row_mask:0xf bank_mask:0xf
	v_fmac_f32_dpp v244, v36, v246 row_ror:15 row_mask:0xf bank_mask:0xf
	v_fmac_f32_dpp v245, v37, v247 row_ror:15 row_mask:0xf bank_mask:0xf
	v_pk_mul_f32 v[144:145], v[242:243], s[6:7] op_sel_hi:[1,0]
	v_pk_mul_f32 v[246:247], v[244:245], s[6:7] op_sel_hi:[1,0]
	v_exp_f32_e32 v144, v144
	v_exp_f32_e32 v145, v145
	v_exp_f32_e32 v246, v246
	v_exp_f32_e32 v247, v247
	v_add_f32_e32 v144, 1.0, v144
	v_add_f32_e32 v145, 1.0, v145
	v_add_f32_e32 v246, 1.0, v246
	v_add_f32_e32 v247, 1.0, v247
	v_rcp_f32_e32 v144, v144
	v_rcp_f32_e32 v145, v145
	v_rcp_f32_e32 v246, v246
	v_rcp_f32_e32 v247, v247
	s_nop 0
	v_pk_mul_f32 v[144:145], v[242:243], v[144:145]
	v_pk_mul_f32 v[246:247], v[244:245], v[246:247]
	v_pk_mul_f32 v[144:145], v[238:239], v[144:145]
	v_pk_mul_f32 v[246:247], v[240:241], v[246:247]
	v_cvt_pk_bf16_f32 v124, v144, v145
	v_cvt_pk_bf16_f32 v125, v246, v247
	s_add_u32 s26, s94, 0x58000
	s_addc_u32 s27, s95, 0
	global_store_dwordx4 v217, v[122:125], s[26:27]
	v_pk_fma_f32 v[238:239], v[146:147], v[54:55], v[102:103]
	v_pk_fma_f32 v[240:241], v[148:149], v[56:57], v[104:105]
	v_pk_fma_f32 v[242:243], v[114:115], v[50:51], v[98:99]
	v_pk_fma_f32 v[244:245], v[116:117], v[52:53], v[100:101]
	v_fmac_f32_dpp v238, v54, v158 row_shr:1 row_mask:0xf bank_mask:0xf
	v_fmac_f32_dpp v239, v55, v159 row_shr:1 row_mask:0xf bank_mask:0xf
	v_fmac_f32_dpp v240, v56, v160 row_shr:1 row_mask:0xf bank_mask:0xf
	v_fmac_f32_dpp v241, v57, v161 row_shr:1 row_mask:0xf bank_mask:0xf
	v_fmac_f32_dpp v242, v50, v154 row_shr:1 row_mask:0xf bank_mask:0xf
	v_fmac_f32_dpp v243, v51, v155 row_shr:1 row_mask:0xf bank_mask:0xf
	v_fmac_f32_dpp v244, v52, v156 row_shr:1 row_mask:0xf bank_mask:0xf
	v_fmac_f32_dpp v245, v53, v157 row_shr:1 row_mask:0xf bank_mask:0xf
	v_fmac_f32_dpp v238, v54, v110 row_shl:1 row_mask:0xf bank_mask:0xf
	v_fmac_f32_dpp v239, v55, v111 row_shl:1 row_mask:0xf bank_mask:0xf
	v_fmac_f32_dpp v240, v56, v112 row_shl:1 row_mask:0xf bank_mask:0xf
	v_fmac_f32_dpp v241, v57, v113 row_shl:1 row_mask:0xf bank_mask:0xf
	v_fmac_f32_dpp v242, v50, v106 row_shl:1 row_mask:0xf bank_mask:0xf
	v_fmac_f32_dpp v243, v51, v107 row_shl:1 row_mask:0xf bank_mask:0xf
	v_fmac_f32_dpp v244, v52, v108 row_shl:1 row_mask:0xf bank_mask:0xf
	v_fmac_f32_dpp v245, v53, v109 row_shl:1 row_mask:0xf bank_mask:0xf
	v_cndmask_b32_e64 v144, 0, v158, s[38:39]
	v_cndmask_b32_e64 v145, 0, v159, s[38:39]
	v_cndmask_b32_e64 v246, 0, v160, s[38:39]
	v_cndmask_b32_e64 v247, 0, v161, s[38:39]
	v_fmac_f32_dpp v238, v62, v144 row_ror:1 row_mask:0xf bank_mask:0xf
	v_fmac_f32_dpp v239, v63, v145 row_ror:1 row_mask:0xf bank_mask:0xf
	v_fmac_f32_dpp v240, v64, v246 row_ror:1 row_mask:0xf bank_mask:0xf
	v_fmac_f32_dpp v241, v65, v247 row_ror:1 row_mask:0xf bank_mask:0xf
	v_cndmask_b32_e64 v144, 0, v154, s[38:39]
	v_cndmask_b32_e64 v145, 0, v155, s[38:39]
	v_cndmask_b32_e64 v246, 0, v156, s[38:39]
	v_cndmask_b32_e64 v247, 0, v157, s[38:39]
	v_fmac_f32_dpp v242, v58, v144 row_ror:1 row_mask:0xf bank_mask:0xf
	v_fmac_f32_dpp v243, v59, v145 row_ror:1 row_mask:0xf bank_mask:0xf
	v_fmac_f32_dpp v244, v60, v246 row_ror:1 row_mask:0xf bank_mask:0xf
	v_fmac_f32_dpp v245, v61, v247 row_ror:1 row_mask:0xf bank_mask:0xf
	v_cndmask_b32_e64 v144, 0, v110, s[40:41]
	v_cndmask_b32_e64 v145, 0, v111, s[40:41]
	v_cndmask_b32_e64 v246, 0, v112, s[40:41]
	v_cndmask_b32_e64 v247, 0, v113, s[40:41]
	v_fmac_f32_dpp v238, v46, v144 row_ror:15 row_mask:0xf bank_mask:0xf
	v_fmac_f32_dpp v239, v47, v145 row_ror:15 row_mask:0xf bank_mask:0xf
	v_fmac_f32_dpp v240, v48, v246 row_ror:15 row_mask:0xf bank_mask:0xf
	v_fmac_f32_dpp v241, v49, v247 row_ror:15 row_mask:0xf bank_mask:0xf
	v_cndmask_b32_e64 v144, 0, v106, s[40:41]
	v_cndmask_b32_e64 v145, 0, v107, s[40:41]
	v_cndmask_b32_e64 v246, 0, v108, s[40:41]
	v_cndmask_b32_e64 v247, 0, v109, s[40:41]
	v_fmac_f32_dpp v242, v42, v144 row_ror:15 row_mask:0xf bank_mask:0xf
	v_fmac_f32_dpp v243, v43, v145 row_ror:15 row_mask:0xf bank_mask:0xf
	v_fmac_f32_dpp v244, v44, v246 row_ror:15 row_mask:0xf bank_mask:0xf
	v_fmac_f32_dpp v245, v45, v247 row_ror:15 row_mask:0xf bank_mask:0xf
	v_pk_mul_f32 v[144:145], v[242:243], s[6:7] op_sel_hi:[1,0]
	v_pk_mul_f32 v[246:247], v[244:245], s[6:7] op_sel_hi:[1,0]
	v_exp_f32_e32 v144, v144
	v_exp_f32_e32 v145, v145
	v_exp_f32_e32 v246, v246
	v_exp_f32_e32 v247, v247
	v_add_f32_e32 v144, 1.0, v144
	v_add_f32_e32 v145, 1.0, v145
	v_add_f32_e32 v246, 1.0, v246
	v_add_f32_e32 v247, 1.0, v247
	v_rcp_f32_e32 v144, v144
	v_rcp_f32_e32 v145, v145
	v_rcp_f32_e32 v246, v246
	v_rcp_f32_e32 v247, v247
	s_nop 0
	v_pk_mul_f32 v[144:145], v[242:243], v[144:145]
	v_pk_mul_f32 v[246:247], v[244:245], v[246:247]
	v_pk_mul_f32 v[144:145], v[238:239], v[144:145]
	v_pk_mul_f32 v[246:247], v[240:241], v[246:247]
	v_cvt_pk_bf16_f32 v122, v144, v145
	v_cvt_pk_bf16_f32 v123, v246, v247
	s_add_u32 s26, s94, 0x2c000
	s_addc_u32 s27, s95, 0
	global_store_dwordx4 v217, v[120:123], s[26:27]
	v_pk_fma_f32 v[238:239], v[146:147], v[62:63], v[102:103]
	v_pk_fma_f32 v[240:241], v[148:149], v[64:65], v[104:105]
	v_pk_fma_f32 v[242:243], v[114:115], v[58:59], v[98:99]
	v_pk_fma_f32 v[244:245], v[116:117], v[60:61], v[100:101]
	v_fmac_f32_dpp v238, v62, v158 row_shr:1 row_mask:0xf bank_mask:0xf
	v_fmac_f32_dpp v239, v63, v159 row_shr:1 row_mask:0xf bank_mask:0xf
	v_fmac_f32_dpp v240, v64, v160 row_shr:1 row_mask:0xf bank_mask:0xf
	v_fmac_f32_dpp v241, v65, v161 row_shr:1 row_mask:0xf bank_mask:0xf
	v_fmac_f32_dpp v242, v58, v154 row_shr:1 row_mask:0xf bank_mask:0xf
	v_fmac_f32_dpp v243, v59, v155 row_shr:1 row_mask:0xf bank_mask:0xf
	v_fmac_f32_dpp v244, v60, v156 row_shr:1 row_mask:0xf bank_mask:0xf
	v_fmac_f32_dpp v245, v61, v157 row_shr:1 row_mask:0xf bank_mask:0xf
	v_fmac_f32_dpp v238, v62, v110 row_shl:1 row_mask:0xf bank_mask:0xf
	v_fmac_f32_dpp v239, v63, v111 row_shl:1 row_mask:0xf bank_mask:0xf
	v_fmac_f32_dpp v240, v64, v112 row_shl:1 row_mask:0xf bank_mask:0xf
	v_fmac_f32_dpp v241, v65, v113 row_shl:1 row_mask:0xf bank_mask:0xf
	v_fmac_f32_dpp v242, v58, v106 row_shl:1 row_mask:0xf bank_mask:0xf
	v_fmac_f32_dpp v243, v59, v107 row_shl:1 row_mask:0xf bank_mask:0xf
	v_fmac_f32_dpp v244, v60, v108 row_shl:1 row_mask:0xf bank_mask:0xf
	v_fmac_f32_dpp v245, v61, v109 row_shl:1 row_mask:0xf bank_mask:0xf
	s_waitcnt lgkmcnt(0)
	s_cmp_eq_u32 s4, 0
	s_cbranch_scc1 .Lupc_7
	v_cndmask_b32_e64 v144, 0, v158, s[38:39]
	v_cndmask_b32_e64 v145, 0, v159, s[38:39]
	v_cndmask_b32_e64 v246, 0, v160, s[38:39]
	v_cndmask_b32_e64 v247, 0, v161, s[38:39]
	v_pk_fma_f32 v[238:239], v[192:193], v[144:145], v[238:239]
	v_pk_fma_f32 v[240:241], v[194:195], v[246:247], v[240:241]
	v_cndmask_b32_e64 v144, 0, v154, s[38:39]
	v_cndmask_b32_e64 v145, 0, v155, s[38:39]
	v_cndmask_b32_e64 v246, 0, v156, s[38:39]
	v_cndmask_b32_e64 v247, 0, v157, s[38:39]
	v_pk_fma_f32 v[242:243], v[212:213], v[144:145], v[242:243]
	v_pk_fma_f32 v[244:245], v[214:215], v[246:247], v[244:245]
.Lupc_7:
	v_cndmask_b32_e64 v144, 0, v110, s[40:41]
	v_cndmask_b32_e64 v145, 0, v111, s[40:41]
	v_cndmask_b32_e64 v246, 0, v112, s[40:41]
	v_cndmask_b32_e64 v247, 0, v113, s[40:41]
	v_fmac_f32_dpp v238, v54, v144 row_ror:15 row_mask:0xf bank_mask:0xf
	v_fmac_f32_dpp v239, v55, v145 row_ror:15 row_mask:0xf bank_mask:0xf
	v_fmac_f32_dpp v240, v56, v246 row_ror:15 row_mask:0xf bank_mask:0xf
	v_fmac_f32_dpp v241, v57, v247 row_ror:15 row_mask:0xf bank_mask:0xf
	v_cndmask_b32_e64 v144, 0, v106, s[40:41]
	v_cndmask_b32_e64 v145, 0, v107, s[40:41]
	v_cndmask_b32_e64 v246, 0, v108, s[40:41]
	v_cndmask_b32_e64 v247, 0, v109, s[40:41]
	v_fmac_f32_dpp v242, v50, v144 row_ror:15 row_mask:0xf bank_mask:0xf
	v_fmac_f32_dpp v243, v51, v145 row_ror:15 row_mask:0xf bank_mask:0xf
	v_fmac_f32_dpp v244, v52, v246 row_ror:15 row_mask:0xf bank_mask:0xf
	v_fmac_f32_dpp v245, v53, v247 row_ror:15 row_mask:0xf bank_mask:0xf
	s_cmp_lg_u32 s4, 0
	s_cbranch_scc1 .Lupc_8
	s_mov_b64 exec, s[38:39]
	s_lshl_b32 s7, s72, 1
	s_mul_i32 s7, s7, 0xb000
	v_readlane_b32 s26, v255, 0
	v_readlane_b32 s27, v255, 1
	s_add_u32 s26, s26, s7
	s_addc_u32 s27, s27, 0
	global_store_dwordx4 v196, v[62:65], s[26:27] offset:16
	s_add_u32 s26, s26, 22528
	s_addc_u32 s27, s27, 0
	global_store_dwordx4 v196, v[58:61], s[26:27] offset:16
	v_readlane_b32 s26, v255, 15
	v_readlane_b32 s27, v255, 16
	s_add_u32 s26, s26, s7
	s_addc_u32 s27, s27, 0
	global_store_dwordx4 v196, v[238:241], s[26:27] offset:16
	s_add_u32 s26, s26, 22528
	s_addc_u32 s27, s27, 0
	global_store_dwordx4 v196, v[242:245], s[26:27] offset:16
	s_mov_b64 exec, -1
.Lupc_8:
	v_pk_mul_f32 v[144:145], v[242:243], s[6:7] op_sel_hi:[1,0]
	v_pk_mul_f32 v[246:247], v[244:245], s[6:7] op_sel_hi:[1,0]
	v_exp_f32_e32 v144, v144
	v_exp_f32_e32 v145, v145
	v_exp_f32_e32 v246, v246
	v_exp_f32_e32 v247, v247
	v_add_f32_e32 v144, 1.0, v144
	v_add_f32_e32 v145, 1.0, v145
	v_add_f32_e32 v246, 1.0, v246
	v_add_f32_e32 v247, 1.0, v247
	v_rcp_f32_e32 v144, v144
	v_rcp_f32_e32 v145, v145
	v_rcp_f32_e32 v246, v246
	v_rcp_f32_e32 v247, v247
	s_nop 0
	v_pk_mul_f32 v[144:145], v[242:243], v[144:145]
	v_pk_mul_f32 v[246:247], v[244:245], v[246:247]
	v_pk_mul_f32 v[144:145], v[238:239], v[144:145]
	v_pk_mul_f32 v[246:247], v[240:241], v[246:247]
	v_cvt_pk_bf16_f32 v120, v144, v145
	v_cvt_pk_bf16_f32 v121, v246, v247
	global_store_dwordx4 v217, v[118:121], s[94:95]
	s_andn2_b64 vcc, exec, s[20:21]
	s_mov_b64 s[4:5], -1
	s_cbranch_vccnz .LBB0_179
	v_readlane_b32 s4, v255, 3
	v_readlane_b32 s5, v255, 4
	s_and_b64 vcc, exec, s[4:5]
	s_cbranch_vccnz .LBB0_178
	s_barrier
	s_branch .LBB0_178
